# scan item prologue: first 13 token loads issued right behind the token-0 load instead of after its full wait
# speedup vs baseline: 1.0044x; 1.0044x over previous
.LBB0_234:
	global_load_ushort v3, v0, s[42:43]
	global_load_ushort v20, v0, s[42:43] offset:2048
	global_load_ushort v17, v73, s[42:43]
	global_load_ushort v16, v75, s[42:43]
	global_load_ushort v15, v82, s[42:43]
	global_load_ushort v14, v83, s[42:43]
	global_load_ushort v13, v84, s[42:43]
	global_load_ushort v12, v85, s[42:43]
	global_load_ushort v10, v86, s[42:43]
	global_load_ushort v9, v87, s[42:43]
	global_load_ushort v7, v88, s[42:43]
	global_load_ushort v6, v89, s[42:43]
	global_load_ushort v5, v90, s[42:43]
	global_load_ushort v4, v91, s[42:43]
	s_waitcnt vmcnt(18)
	v_mul_f32_e32 v2, v141, v2
	s_waitcnt vmcnt(17)
	v_fmac_f32_e32 v2, v144, v18
	s_lshl_b64 s[28:29], s[0:1], 1
	v_readlane_b32 s0, v251, 5
	s_waitcnt vmcnt(16)
	v_fmac_f32_e32 v2, v143, v8
	v_readlane_b32 s1, v251, 6
	s_add_u32 s0, s0, s28
	s_addc_u32 s1, s1, s29
	v_mul_f32_e32 v18, v141, v18
	v_add_u32_e32 v127, v53, v27
	v_fmac_f32_e32 v18, v144, v8
	s_add_u32 s38, s60, s28
	s_mov_b32 s30, 0x3fb8aa3b
	s_mov_b32 s28, 0x3c088889
	s_mov_b32 s36, 0x3ab60b61
	s_mov_b32 s40, 0x3d2aaaab
	s_mov_b32 s44, 0x3e2aaaab
	s_mov_b32 s25, 0xbe800000
	v_add_u32_e32 v174, 0x800, v59
	v_add_u32_e32 v148, 0xa00, v59
	v_add_u32_e32 v167, 0x1c00, v59
	v_add_u32_e32 v168, 32, v61
	v_add_u32_e32 v170, 32, v63
	v_add_u32_e32 v155, 32, v67
	s_addc_u32 s39, s61, s29
	v_add_u32_e32 v176, 0xe0, v71
	v_add_u32_e32 v175, 0xf0, v71
	s_waitcnt vmcnt(13)
	v_lshlrev_b32_e32 v11, 16, v3
	v_fmac_f32_e32 v2, v128, v11
	v_add_f32_e32 v19, v129, v2
	global_load_ushort v3, v92, s[42:43]
	global_load_ushort v2, v93, s[42:43]
	global_load_ushort v78, v0, s[0:1]
	global_load_ushort v79, v0, s[0:1] offset:2048
	global_load_ushort v172, v73, s[0:1]
	global_load_ushort v173, v75, s[0:1]
	global_load_ushort v169, v82, s[0:1]
	global_load_ushort v171, v83, s[0:1]
	global_load_ushort v158, v84, s[0:1]
	global_load_ushort v159, v85, s[0:1]
	global_load_ushort v156, v86, s[0:1]
	global_load_ushort v157, v87, s[0:1]
	global_load_ushort v151, v88, s[0:1]
	global_load_ushort v154, v89, s[0:1]
	global_load_ushort v149, v90, s[0:1]
	global_load_ushort v150, v91, s[0:1]
	global_load_ushort v80, v92, s[0:1]
	global_load_ushort v81, v93, s[0:1]
	global_load_ushort v193, v94, s[42:43]
	global_load_ushort v223, v95, s[42:43]
	global_load_ushort v222, v96, s[42:43]
	global_load_ushort v221, v97, s[42:43]
	global_load_ushort v220, v98, s[42:43]
	global_load_ushort v219, v99, s[42:43]
	global_load_ushort v218, v100, s[42:43]
	global_load_ushort v217, v101, s[42:43]
	global_load_ushort v216, v102, s[42:43]
	global_load_ushort v215, v103, s[42:43]
	global_load_ushort v214, v104, s[42:43]
	global_load_ushort v213, v105, s[42:43]
	global_load_ushort v212, v106, s[42:43]
	global_load_ushort v211, v107, s[42:43]
	global_load_ushort v210, v108, s[42:43]
	global_load_ushort v209, v109, s[42:43]
	global_load_ushort v191, v94, s[0:1]
	global_load_ushort v192, v95, s[0:1]
	global_load_ushort v189, v96, s[0:1]
	global_load_ushort v190, v97, s[0:1]
	global_load_ushort v187, v98, s[0:1]
	global_load_ushort v188, v99, s[0:1]
	global_load_ushort v185, v100, s[0:1]
	global_load_ushort v186, v101, s[0:1]
	global_load_ushort v183, v102, s[0:1]
	global_load_ushort v184, v103, s[0:1]
	global_load_ushort v181, v104, s[0:1]
	global_load_ushort v182, v105, s[0:1]
	global_load_ushort v179, v106, s[0:1]
	global_load_ushort v180, v107, s[0:1]
	global_load_ushort v177, v108, s[0:1]
	global_load_ushort v178, v109, s[0:1]
	v_cvt_pk_bf16_f32 v21, v19, v1
	ds_write_b32 v127, v19 offset:2304
	v_fmac_f32_e32 v18, v143, v11
	ds_write_b16 v53, v21
	s_waitcnt vmcnt(62)
	v_lshlrev_b32_e32 v19, 16, v20
	v_fmac_f32_e32 v18, v128, v19
	v_add_f32_e32 v18, v129, v18
	v_cvt_pk_bf16_f32 v20, v18, v1
	ds_write_b16 v53, v20 offset:144
	ds_write_b32 v127, v18 offset:2576
	v_mul_f32_e32 v18, v144, v11
	v_fmac_f32_e32 v18, v141, v8
	s_waitcnt vmcnt(61)
	v_lshlrev_b32_e32 v17, 16, v17
	v_fmac_f32_e32 v18, v143, v19
	v_fmac_f32_e32 v18, v128, v17
	v_add_f32_e32 v8, v129, v18
	v_cvt_pk_bf16_f32 v18, v8, v1
	ds_write_b16 v53, v18 offset:288
	ds_write_b32 v127, v8 offset:2848
	s_waitcnt vmcnt(60)
	v_lshlrev_b32_e32 v8, 16, v16
	v_mul_f32_e32 v16, v144, v19
	v_fmac_f32_e32 v16, v141, v11
	v_fmac_f32_e32 v16, v143, v17
	v_fmac_f32_e32 v16, v128, v8
	v_add_f32_e32 v11, v129, v16
	v_cvt_pk_bf16_f32 v16, v11, v1
	ds_write_b16 v53, v16 offset:432
	ds_write_b32 v127, v11 offset:3120
	s_waitcnt vmcnt(59)
	v_lshlrev_b32_e32 v11, 16, v15
	v_mul_f32_e32 v15, v144, v17
	v_fmac_f32_e32 v15, v141, v19
	v_fmac_f32_e32 v15, v143, v8
	v_fmac_f32_e32 v15, v128, v11
	v_add_f32_e32 v15, v129, v15
	v_cvt_pk_bf16_f32 v16, v15, v1
	ds_write_b16 v53, v16 offset:576
	ds_write_b32 v127, v15 offset:3392
	v_mul_f32_e32 v15, v144, v8
	v_fmac_f32_e32 v15, v141, v17
	s_waitcnt vmcnt(58)
	v_lshlrev_b32_e32 v14, 16, v14
	v_fmac_f32_e32 v15, v143, v11
	v_fmac_f32_e32 v15, v128, v14
	v_add_f32_e32 v15, v129, v15
	v_cvt_pk_bf16_f32 v16, v15, v1
	ds_write_b16 v53, v16 offset:720
	ds_write_b32 v127, v15 offset:3664
	v_mul_f32_e32 v15, v144, v11
	v_fmac_f32_e32 v15, v141, v8
	s_waitcnt vmcnt(57)
	v_lshlrev_b32_e32 v13, 16, v13
	v_fmac_f32_e32 v15, v143, v14
	v_fmac_f32_e32 v15, v128, v13
	v_add_f32_e32 v8, v129, v15
	v_cvt_pk_bf16_f32 v15, v8, v1
	ds_write_b16 v53, v15 offset:864
	ds_write_b32 v127, v8 offset:3936
	s_waitcnt vmcnt(56)
	v_lshlrev_b32_e32 v8, 16, v12
	v_mul_f32_e32 v12, v144, v14
	v_fmac_f32_e32 v12, v141, v11
	v_fmac_f32_e32 v12, v143, v13
	v_fmac_f32_e32 v12, v128, v8
	v_add_f32_e32 v11, v129, v12
	v_cvt_pk_bf16_f32 v12, v11, v1
	ds_write_b16 v53, v12 offset:1008
	ds_write_b32 v127, v11 offset:4208
	v_mul_f32_e32 v11, v144, v13
	v_fmac_f32_e32 v11, v141, v14
	s_waitcnt vmcnt(55)
	v_lshlrev_b32_e32 v10, 16, v10
	v_fmac_f32_e32 v11, v143, v8
	v_fmac_f32_e32 v11, v128, v10
	v_add_f32_e32 v11, v129, v11
	v_cvt_pk_bf16_f32 v12, v11, v1
	ds_write_b16 v53, v12 offset:1152
	ds_write_b32 v127, v11 offset:4480
	v_mul_f32_e32 v11, v144, v8
	v_fmac_f32_e32 v11, v141, v13
	s_waitcnt vmcnt(54)
	v_lshlrev_b32_e32 v9, 16, v9
	v_fmac_f32_e32 v11, v143, v10
	v_fmac_f32_e32 v11, v128, v9
	v_add_f32_e32 v11, v129, v11
	v_cvt_pk_bf16_f32 v12, v11, v1
	ds_write_b16 v53, v12 offset:1296
	ds_write_b32 v127, v11 offset:4752
	v_mul_f32_e32 v11, v144, v10
	v_fmac_f32_e32 v11, v141, v8
	s_waitcnt vmcnt(53)
	v_lshlrev_b32_e32 v7, 16, v7
	v_fmac_f32_e32 v11, v143, v9
	v_fmac_f32_e32 v11, v128, v7
	v_add_f32_e32 v8, v129, v11
	v_cvt_pk_bf16_f32 v11, v8, v1
	ds_write_b16 v53, v11 offset:1440
	ds_write_b32 v127, v8 offset:5024
	v_mul_f32_e32 v8, v144, v9
	v_fmac_f32_e32 v8, v141, v10
	s_waitcnt vmcnt(52)
	v_lshlrev_b32_e32 v6, 16, v6
	v_fmac_f32_e32 v8, v143, v7
	v_fmac_f32_e32 v8, v128, v6
	v_add_f32_e32 v8, v129, v8
	v_cvt_pk_bf16_f32 v10, v8, v1
	ds_write_b16 v53, v10 offset:1584
	ds_write_b32 v127, v8 offset:5296
	v_mul_f32_e32 v8, v144, v7
	s_waitcnt vmcnt(51)
	v_lshlrev_b32_e32 v5, 16, v5
	v_fmac_f32_e32 v8, v141, v9
	s_waitcnt vmcnt(50)
	v_lshlrev_b32_e32 v194, 16, v4
	v_mul_f32_e32 v4, v144, v6
	v_fmac_f32_e32 v8, v143, v6
	v_fmac_f32_e32 v4, v141, v7
	s_waitcnt vmcnt(49)
	v_lshlrev_b32_e32 v240, 16, v3
	v_mul_f32_e32 v3, v144, v5
	v_fmac_f32_e32 v8, v128, v5
	v_fmac_f32_e32 v4, v143, v5
	v_fmac_f32_e32 v3, v141, v6
	s_waitcnt vmcnt(48)
	v_lshlrev_b32_e32 v241, 16, v2
	v_mul_f32_e32 v2, v144, v194
	v_add_f32_e32 v8, v129, v8
	v_cvt_pk_bf16_f32 v9, v8, v1
	v_fmac_f32_e32 v4, v128, v194
	v_fmac_f32_e32 v3, v143, v194
	v_fmac_f32_e32 v2, v141, v5
	ds_write_b16 v53, v9 offset:1728
	ds_write_b32 v127, v8 offset:5568
	v_add_f32_e32 v4, v129, v4
	v_cvt_pk_bf16_f32 v7, v4, v1
	v_fmac_f32_e32 v3, v128, v240
	v_fmac_f32_e32 v2, v143, v240
	ds_write_b16 v53, v7 offset:1872
	ds_write_b32 v127, v4 offset:5840
	v_add_f32_e32 v3, v129, v3
	v_cvt_pk_bf16_f32 v4, v3, v1
	v_fmac_f32_e32 v2, v128, v241
	ds_write_b16 v53, v4 offset:2016
	ds_write_b32 v127, v3 offset:6112
	v_add_f32_e32 v2, v129, v2
	v_cvt_pk_bf16_f32 v3, v2, v1
	ds_write_b16 v53, v3 offset:2160
	ds_write_b32 v127, v2 offset:6384
	ds_read_b128 v[2:5], v57
	ds_read_b128 v[196:199], v57 offset:64
	ds_read_b128 v[6:9], v110
	ds_read_b128 v[10:13], v110 offset:64
	ds_read_b128 v[14:17], v110 offset:9216
	ds_read_b128 v[18:21], v110 offset:9280
	s_waitcnt lgkmcnt(3)
	v_mfma_f32_16x16x32_bf16 v[6:9], v[2:5], v[6:9], 0
	s_waitcnt vmcnt(18)
	v_lshlrev_b32_e32 v211, 16, v211
	s_waitcnt vmcnt(17)
	v_lshlrev_b32_e32 v210, 16, v210
	s_waitcnt vmcnt(16)
	v_lshlrev_b32_e32 v209, 16, v209
	s_waitcnt lgkmcnt(2)
	v_mfma_f32_16x16x32_bf16 v[200:203], v[196:199], v[10:13], v[6:9]
	s_waitcnt lgkmcnt(1)
	v_mfma_f32_16x16x32_bf16 v[6:9], v[2:5], v[14:17], 0
	s_waitcnt lgkmcnt(0)
	v_mfma_f32_16x16x32_bf16 v[204:207], v[196:199], v[18:21], v[6:9]
	s_nop 3
	v_add_f32_e64 v76, v72, v200
	v_add_f32_e64 v77, v72, v201
	v_pk_mul_f32 v[76:77], v[76:77], s[34:35] op_sel_hi:[1,0]
	ds_read_b128 v[6:9], v110 offset:2304
	ds_read_b128 v[10:13], v110 offset:2368
	ds_read_b128 v[14:17], v110 offset:11520
	ds_read_b128 v[22:25], v110 offset:11584
	v_exp_f32_e32 v76, v76
	v_exp_f32_e32 v77, v77
	s_waitcnt lgkmcnt(3)
	v_mfma_f32_16x16x32_bf16 v[6:9], v[2:5], v[6:9], 0
	v_add_f32_e64 v130, v74, v204
	v_add_f32_e64 v131, v74, v205
	v_pk_mul_f32 v[130:131], v[130:131], s[34:35] op_sel_hi:[1,0]
	v_pk_add_f32 v[76:77], v[76:77], 1.0 op_sel_hi:[1,0]
	s_waitcnt lgkmcnt(2)
	v_mfma_f32_16x16x32_bf16 v[18:21], v[196:199], v[10:13], v[6:9]
	v_rcp_f32_e32 v76, v76
	v_rcp_f32_e32 v77, v77
	v_exp_f32_e32 v130, v130
	s_waitcnt lgkmcnt(1)
	v_mfma_f32_16x16x32_bf16 v[6:9], v[2:5], v[14:17], 0
	v_exp_f32_e32 v131, v131
	v_pk_mul_f32 v[76:77], v[70:71], v[76:77] op_sel_hi:[0,1]
	v_pk_mul_f32 v[132:133], v[76:77], s[30:31] op_sel_hi:[1,0]
	v_pk_add_f32 v[146:147], v[76:77], v[76:77]
	v_mov_b64_e32 v[76:77], s[28:29]
	v_pk_fma_f32 v[152:153], v[146:147], s[36:37], v[76:77] op_sel_hi:[1,0,0]
	v_exp_f32_e32 v132, v132
	v_exp_f32_e32 v133, v133
	v_pk_fma_f32 v[152:153], v[146:147], v[152:153], s[40:41] op_sel_hi:[1,1,0]
	s_waitcnt lgkmcnt(0)
	v_mfma_f32_16x16x32_bf16 v[22:25], v[196:199], v[22:25], v[6:9]
	s_nop 2
	ds_read_b128 v[6:9], v110 offset:4608
	ds_read_b128 v[10:13], v110 offset:4672
	ds_read_b128 v[14:17], v110 offset:13824
	ds_read_b128 v[224:227], v110 offset:13888
	v_pk_fma_f32 v[152:153], v[146:147], v[152:153], s[44:45] op_sel_hi:[1,1,0]
	v_pk_fma_f32 v[162:163], v[132:133], v[132:133], 1.0 op_sel_hi:[1,1,0] neg_lo:[1,0,0] neg_hi:[1,0,0]
	v_pk_fma_f32 v[152:153], v[146:147], v[152:153], 0.5 op_sel_hi:[1,1,0]
	s_waitcnt lgkmcnt(3)
	v_mfma_f32_16x16x32_bf16 v[6:9], v[2:5], v[6:9], 0
	v_fma_f32 v152, v146, v152, 1.0
	v_fma_f32 v153, v147, v153, 1.0
	v_cmp_lt_f32_e32 vcc, s25, v146
	v_pk_mul_f32 v[152:153], v[152:153], v[146:147] neg_lo:[0,1] neg_hi:[0,1]
	v_pk_add_f32 v[130:131], v[130:131], 1.0 op_sel_hi:[1,0]
	v_cndmask_b32_e32 v145, v162, v152, vcc
	v_cmp_lt_f32_e32 vcc, s25, v147
	v_sqrt_f32_e32 v146, v145
	s_waitcnt lgkmcnt(2)
	v_mfma_f32_16x16x32_bf16 v[10:13], v[196:199], v[10:13], v[6:9]
	v_cndmask_b32_e32 v145, v163, v153, vcc
	v_rcp_f32_e32 v130, v130
	v_rcp_f32_e32 v131, v131
	s_waitcnt lgkmcnt(1)
	v_mfma_f32_16x16x32_bf16 v[6:9], v[2:5], v[14:17], 0
	v_sqrt_f32_e32 v147, v145
	v_pk_add_f32 v[18:19], v[66:67], v[18:19] op_sel_hi:[0,1]
	v_pk_mul_f32 v[18:19], v[18:19], s[34:35] op_sel_hi:[1,0]
	s_waitcnt lgkmcnt(0)
	v_mfma_f32_16x16x32_bf16 v[14:17], v[196:199], v[224:227], v[6:9]
	s_nop 2
	ds_read_b128 v[6:9], v110 offset:6912
	ds_read_b128 v[224:227], v110 offset:6976
	ds_read_b128 v[228:231], v110 offset:16128
	ds_read_b128 v[232:235], v110 offset:16192
	v_pk_mul_f32 v[130:131], v[130:131], v[146:147]
	ds_read2_b32 v[146:147], v174 offset0:64 offset1:80
	ds_read2_b32 v[152:153], v174 offset0:132 offset1:148
	s_waitcnt lgkmcnt(5)
	v_mfma_f32_16x16x32_bf16 v[6:9], v[2:5], v[6:9], 0
	v_exp_f32_e32 v18, v18
	v_exp_f32_e32 v19, v19
	s_waitcnt lgkmcnt(1)
	v_mov_b32_e32 v162, v146
	s_waitcnt lgkmcnt(0)
	v_mov_b32_e32 v163, v152
	v_pk_mul_f32 v[130:131], v[162:163], v[130:131]
	ds_write_b32 v59, v130 offset:2304
	ds_write_b32 v59, v131 offset:2576
	ds_write_b32 v59, v132 offset:6656
	ds_write_b32 v59, v133 offset:6928
	v_pk_add_f32 v[130:131], v[72:73], v[202:203] op_sel_hi:[0,1]
	v_pk_mul_f32 v[130:131], v[130:131], s[34:35] op_sel_hi:[1,0]
	v_mfma_f32_16x16x32_bf16 v[2:5], v[2:5], v[228:231], 0
	v_exp_f32_e32 v130, v130
	v_exp_f32_e32 v131, v131
	v_pk_add_f32 v[132:133], v[74:75], v[206:207] op_sel_hi:[0,1]
	v_pk_mul_f32 v[132:133], v[132:133], s[34:35] op_sel_hi:[1,0]
	v_mfma_f32_16x16x32_bf16 v[6:9], v[196:199], v[224:227], v[6:9]
	v_add_f32_e64 v130, v130, 1.0
	v_add_f32_e64 v131, v131, 1.0
	v_exp_f32_e32 v132, v132
	v_rcp_f32_e32 v130, v130
	v_rcp_f32_e32 v131, v131
	v_exp_f32_e32 v133, v133
	v_mfma_f32_16x16x32_bf16 v[2:5], v[196:199], v[232:235], v[2:5]
	v_add_f32_e64 v18, v18, 1.0
	v_add_f32_e64 v19, v19, 1.0
	v_pk_mul_f32 v[130:131], v[70:71], v[130:131] op_sel_hi:[0,1]
	v_pk_mul_f32 v[162:163], v[130:131], s[30:31] op_sel_hi:[1,0]
	v_pk_add_f32 v[130:131], v[130:131], v[130:131]
	v_exp_f32_e32 v162, v162
	v_pk_fma_f32 v[164:165], v[130:131], s[36:37], v[76:77] op_sel_hi:[1,0,0]
	v_exp_f32_e32 v163, v163
	v_pk_fma_f32 v[164:165], v[130:131], v[164:165], s[40:41] op_sel_hi:[1,1,0]
	v_cmp_lt_f32_e32 vcc, s25, v130
	v_pk_fma_f32 v[164:165], v[130:131], v[164:165], s[44:45] op_sel_hi:[1,1,0]
	v_pk_fma_f32 v[196:197], v[162:163], v[162:163], 1.0 op_sel_hi:[1,1,0] neg_lo:[1,0,0] neg_hi:[1,0,0]
	v_pk_fma_f32 v[164:165], v[130:131], v[164:165], 0.5 op_sel_hi:[1,1,0]
	v_pk_add_f32 v[132:133], v[132:133], 1.0 op_sel_hi:[1,0]
	v_pk_fma_f32 v[164:165], v[130:131], v[164:165], 1.0 op_sel_hi:[1,1,0]
	v_rcp_f32_e32 v132, v132
	v_pk_mul_f32 v[164:165], v[164:165], v[130:131] neg_lo:[0,1] neg_hi:[0,1]
	v_rcp_f32_e32 v133, v133
	v_cndmask_b32_e32 v130, v196, v164, vcc
	v_cmp_lt_f32_e32 vcc, s25, v131
	v_sqrt_f32_e32 v130, v130
	v_rcp_f32_e32 v18, v18
	v_cndmask_b32_e32 v131, v197, v165, vcc
	v_sqrt_f32_e32 v131, v131
	v_rcp_f32_e32 v19, v19
	v_pk_add_f32 v[22:23], v[68:69], v[22:23] op_sel_hi:[0,1]
	v_pk_mul_f32 v[22:23], v[22:23], s[34:35] op_sel_hi:[1,0]
	v_pk_mul_f32 v[130:131], v[132:133], v[130:131]
	ds_read2_b32 v[132:133], v148 offset0:72 offset1:140
	v_pk_mul_f32 v[18:19], v[64:65], v[18:19] op_sel_hi:[0,1]
	v_exp_f32_e32 v22, v22
	v_exp_f32_e32 v23, v23
	ds_write2_b32 v167, v162, v163 offset0:8 offset1:76
	s_waitcnt lgkmcnt(1)
	v_pk_mul_f32 v[130:131], v[130:131], v[132:133]
	ds_write2_b32 v148, v130, v131 offset0:72 offset1:140
	v_pk_mul_f32 v[130:131], v[18:19], s[30:31] op_sel_hi:[1,0]
	v_pk_add_f32 v[18:19], v[18:19], v[18:19]
	v_exp_f32_e32 v130, v130
	v_pk_fma_f32 v[132:133], v[18:19], s[36:37], v[76:77] op_sel_hi:[1,0,0]
	v_exp_f32_e32 v131, v131
	v_pk_fma_f32 v[132:133], v[18:19], v[132:133], s[40:41] op_sel_hi:[1,1,0]
	v_cmp_lt_f32_e32 vcc, s25, v18
	v_pk_fma_f32 v[132:133], v[18:19], v[132:133], s[44:45] op_sel_hi:[1,1,0]
	v_pk_fma_f32 v[162:163], v[130:131], v[130:131], 1.0 op_sel_hi:[1,1,0] neg_lo:[1,0,0] neg_hi:[1,0,0]
	v_pk_fma_f32 v[132:133], v[18:19], v[132:133], 0.5 op_sel_hi:[1,1,0]
	v_pk_add_f32 v[22:23], v[22:23], 1.0 op_sel_hi:[1,0]
	v_pk_fma_f32 v[132:133], v[18:19], v[132:133], 1.0 op_sel_hi:[1,1,0]
	v_rcp_f32_e32 v22, v22
	v_pk_mul_f32 v[132:133], v[132:133], v[18:19] neg_lo:[0,1] neg_hi:[0,1]
	v_rcp_f32_e32 v23, v23
	v_cndmask_b32_e32 v18, v162, v132, vcc
	v_cmp_lt_f32_e32 vcc, s25, v19
	v_sqrt_f32_e32 v18, v18
	v_mov_b32_e32 v152, v147
	v_cndmask_b32_e32 v19, v163, v133, vcc
	v_sqrt_f32_e32 v19, v19
	v_pk_add_f32 v[10:11], v[60:61], v[10:11] op_sel_hi:[0,1]
	v_pk_mul_f32 v[10:11], v[10:11], s[34:35] op_sel_hi:[1,0]
	v_pk_add_f32 v[14:15], v[62:63], v[14:15] op_sel_hi:[0,1]
	v_pk_mul_f32 v[18:19], v[22:23], v[18:19]
	v_exp_f32_e32 v10, v10
	v_pk_mul_f32 v[18:19], v[18:19], v[152:153]
	ds_write_b32 v59, v18 offset:2368
	ds_write_b32 v59, v19 offset:2640
	ds_write_b32 v59, v130 offset:6720
	ds_write_b32 v59, v131 offset:6992
	v_pk_add_f32 v[18:19], v[66:67], v[20:21] op_sel_hi:[0,1]
	v_pk_mul_f32 v[18:19], v[18:19], s[34:35] op_sel_hi:[1,0]
	v_pk_add_f32 v[20:21], v[68:69], v[24:25] op_sel_hi:[0,1]
	v_exp_f32_e32 v18, v18
	v_exp_f32_e32 v19, v19
	v_pk_mul_f32 v[20:21], v[20:21], s[34:35] op_sel_hi:[1,0]
	v_exp_f32_e32 v11, v11
	v_exp_f32_e32 v20, v20
	v_pk_add_f32 v[18:19], v[18:19], 1.0 op_sel_hi:[1,0]
	v_exp_f32_e32 v21, v21
	v_rcp_f32_e32 v18, v18
	v_rcp_f32_e32 v19, v19
	v_pk_add_f32 v[10:11], v[10:11], 1.0 op_sel_hi:[1,0]
	v_pk_add_f32 v[20:21], v[20:21], 1.0 op_sel_hi:[1,0]
	v_rcp_f32_e32 v10, v10
	v_pk_mul_f32 v[18:19], v[64:65], v[18:19] op_sel_hi:[0,1]
	v_pk_mul_f32 v[22:23], v[18:19], s[30:31] op_sel_hi:[1,0]
	v_pk_add_f32 v[18:19], v[18:19], v[18:19]
	v_exp_f32_e32 v22, v22
	v_pk_fma_f32 v[24:25], v[18:19], s[36:37], v[76:77] op_sel_hi:[1,0,0]
	v_exp_f32_e32 v23, v23
	v_pk_fma_f32 v[24:25], v[18:19], v[24:25], s[40:41] op_sel_hi:[1,1,0]
	v_cmp_lt_f32_e32 vcc, s25, v18
	v_pk_fma_f32 v[24:25], v[18:19], v[24:25], s[44:45] op_sel_hi:[1,1,0]
	v_pk_fma_f32 v[130:131], v[22:23], v[22:23], 1.0 op_sel_hi:[1,1,0] neg_lo:[1,0,0] neg_hi:[1,0,0]
	v_pk_fma_f32 v[24:25], v[18:19], v[24:25], 0.5 op_sel_hi:[1,1,0]
	v_rcp_f32_e32 v20, v20
	v_pk_fma_f32 v[24:25], v[18:19], v[24:25], 1.0 op_sel_hi:[1,1,0]
	v_rcp_f32_e32 v21, v21
	v_pk_mul_f32 v[24:25], v[24:25], v[18:19] neg_lo:[0,1] neg_hi:[0,1]
	v_rcp_f32_e32 v11, v11
	v_cndmask_b32_e32 v18, v130, v24, vcc
	v_cmp_lt_f32_e32 vcc, s25, v19
	v_sqrt_f32_e32 v18, v18
	v_pk_mul_f32 v[10:11], v[58:59], v[10:11] op_sel_hi:[0,1]
	v_cndmask_b32_e32 v19, v131, v25, vcc
	v_sqrt_f32_e32 v19, v19
	v_pk_mul_f32 v[14:15], v[14:15], s[34:35] op_sel_hi:[1,0]
	v_pk_add_f32 v[6:7], v[54:55], v[6:7] op_sel_hi:[0,1]
	v_exp_f32_e32 v14, v14
	v_pk_mul_f32 v[18:19], v[20:21], v[18:19]
	ds_read_b32 v20, v61 offset:2848
	ds_read_b32 v21, v63 offset:2848
	v_exp_f32_e32 v15, v15
	v_pk_mul_f32 v[6:7], v[6:7], s[34:35] op_sel_hi:[1,0]
	v_add_u32_e32 v152, 32, v65
	v_exp_f32_e32 v6, v6
	s_waitcnt lgkmcnt(0)
	v_pk_mul_f32 v[18:19], v[18:19], v[20:21]
	ds_write2st64_b32 v168, v18, v22 offset0:11 offset1:28
	ds_write2st64_b32 v170, v19, v23 offset0:11 offset1:28
	v_pk_mul_f32 v[18:19], v[10:11], s[30:31] op_sel_hi:[1,0]
	v_pk_add_f32 v[10:11], v[10:11], v[10:11]
	v_exp_f32_e32 v18, v18
	v_pk_fma_f32 v[20:21], v[10:11], s[36:37], v[76:77] op_sel_hi:[1,0,0]
	v_exp_f32_e32 v19, v19
	v_pk_fma_f32 v[20:21], v[10:11], v[20:21], s[40:41] op_sel_hi:[1,1,0]
	v_cmp_lt_f32_e32 vcc, s25, v10
	v_pk_fma_f32 v[20:21], v[10:11], v[20:21], s[44:45] op_sel_hi:[1,1,0]
	v_pk_fma_f32 v[22:23], v[18:19], v[18:19], 1.0 op_sel_hi:[1,1,0] neg_lo:[1,0,0] neg_hi:[1,0,0]
	v_pk_fma_f32 v[20:21], v[10:11], v[20:21], 0.5 op_sel_hi:[1,1,0]
	v_pk_add_f32 v[14:15], v[14:15], 1.0 op_sel_hi:[1,0]
	v_pk_fma_f32 v[20:21], v[10:11], v[20:21], 1.0 op_sel_hi:[1,1,0]
	v_rcp_f32_e32 v14, v14
	v_pk_mul_f32 v[20:21], v[20:21], v[10:11] neg_lo:[0,1] neg_hi:[0,1]
	v_rcp_f32_e32 v15, v15
	v_cndmask_b32_e32 v10, v22, v20, vcc
	v_cmp_lt_f32_e32 vcc, s25, v11
	v_sqrt_f32_e32 v10, v10
	v_exp_f32_e32 v7, v7
	v_cndmask_b32_e32 v11, v23, v21, vcc
	v_sqrt_f32_e32 v11, v11
	v_pk_add_f32 v[2:3], v[56:57], v[2:3] op_sel_hi:[0,1]
	v_pk_add_f32 v[6:7], v[6:7], 1.0 op_sel_hi:[1,0]
	v_pk_mul_f32 v[2:3], v[2:3], s[34:35] op_sel_hi:[1,0]
	v_pk_mul_f32 v[10:11], v[14:15], v[10:11]
	ds_read_b32 v14, v59 offset:2432
	ds_read_b32 v15, v59 offset:2704
	v_rcp_f32_e32 v6, v6
	v_rcp_f32_e32 v7, v7
	v_exp_f32_e32 v2, v2
	v_exp_f32_e32 v3, v3
	s_waitcnt lgkmcnt(0)
	v_pk_mul_f32 v[10:11], v[10:11], v[14:15]
	ds_write_b32 v59, v10 offset:2432
	ds_write_b32 v59, v11 offset:2704
	ds_write_b32 v59, v18 offset:6784
	ds_write_b32 v59, v19 offset:7056
	v_pk_add_f32 v[10:11], v[60:61], v[12:13] op_sel_hi:[0,1]
	v_pk_mul_f32 v[10:11], v[10:11], s[34:35] op_sel_hi:[1,0]
	v_pk_add_f32 v[12:13], v[62:63], v[16:17] op_sel_hi:[0,1]
	v_exp_f32_e32 v10, v10
	v_exp_f32_e32 v11, v11
	v_pk_mul_f32 v[12:13], v[12:13], s[34:35] op_sel_hi:[1,0]
	v_pk_mul_f32 v[6:7], v[52:53], v[6:7] op_sel_hi:[0,1]
	v_exp_f32_e32 v12, v12
	v_pk_add_f32 v[10:11], v[10:11], 1.0 op_sel_hi:[1,0]
	v_exp_f32_e32 v13, v13
	v_rcp_f32_e32 v10, v10
	v_rcp_f32_e32 v11, v11
	v_pk_add_f32 v[2:3], v[2:3], 1.0 op_sel_hi:[1,0]
	v_pk_add_f32 v[12:13], v[12:13], 1.0 op_sel_hi:[1,0]
	v_rcp_f32_e32 v2, v2
	v_pk_mul_f32 v[10:11], v[58:59], v[10:11] op_sel_hi:[0,1]
	v_pk_mul_f32 v[14:15], v[10:11], s[30:31] op_sel_hi:[1,0]
	v_pk_add_f32 v[10:11], v[10:11], v[10:11]
	v_exp_f32_e32 v14, v14
	v_pk_fma_f32 v[16:17], v[10:11], s[36:37], v[76:77] op_sel_hi:[1,0,0]
	v_exp_f32_e32 v15, v15
	v_pk_fma_f32 v[16:17], v[10:11], v[16:17], s[40:41] op_sel_hi:[1,1,0]
	v_cmp_lt_f32_e32 vcc, s25, v10
	v_pk_fma_f32 v[16:17], v[10:11], v[16:17], s[44:45] op_sel_hi:[1,1,0]
	v_pk_fma_f32 v[18:19], v[14:15], v[14:15], 1.0 op_sel_hi:[1,1,0] neg_lo:[1,0,0] neg_hi:[1,0,0]
	v_pk_fma_f32 v[16:17], v[10:11], v[16:17], 0.5 op_sel_hi:[1,1,0]
	v_rcp_f32_e32 v12, v12
	v_pk_fma_f32 v[16:17], v[10:11], v[16:17], 1.0 op_sel_hi:[1,1,0]
	v_rcp_f32_e32 v13, v13
	v_pk_mul_f32 v[16:17], v[16:17], v[10:11] neg_lo:[0,1] neg_hi:[0,1]
	v_rcp_f32_e32 v3, v3
	v_cndmask_b32_e32 v10, v18, v16, vcc
	v_cmp_lt_f32_e32 vcc, s25, v11
	v_sqrt_f32_e32 v10, v10
	v_add_u32_e32 v147, 0x800, v69
	v_cndmask_b32_e32 v11, v19, v17, vcc
	v_sqrt_f32_e32 v11, v11
	v_pk_add_f32 v[4:5], v[56:57], v[4:5] op_sel_hi:[0,1]
	v_pk_mul_f32 v[4:5], v[4:5], s[34:35] op_sel_hi:[1,0]
	v_add_u32_e32 v153, 0x1800, v69
	v_pk_mul_f32 v[10:11], v[12:13], v[10:11]
	ds_read_b32 v12, v65 offset:2848
	ds_read_b32 v13, v67 offset:2848
	v_exp_f32_e32 v4, v4
	v_exp_f32_e32 v5, v5
	v_add_u32_e32 v145, 0xa00, v69
	s_mov_b32 s28, 0xc0135761
	s_waitcnt lgkmcnt(0)
	v_pk_mul_f32 v[10:11], v[10:11], v[12:13]
	ds_write2st64_b32 v152, v10, v14 offset0:11 offset1:28
	ds_write2st64_b32 v155, v11, v15 offset0:11 offset1:28
	v_pk_mul_f32 v[10:11], v[6:7], s[30:31] op_sel_hi:[1,0]
	v_pk_add_f32 v[6:7], v[6:7], v[6:7]
	v_exp_f32_e32 v10, v10
	v_pk_fma_f32 v[12:13], v[6:7], s[36:37], v[76:77] op_sel_hi:[1,0,0]
	v_exp_f32_e32 v11, v11
	v_pk_fma_f32 v[12:13], v[6:7], v[12:13], s[40:41] op_sel_hi:[1,1,0]
	v_cmp_lt_f32_e32 vcc, s25, v6
	v_pk_fma_f32 v[12:13], v[6:7], v[12:13], s[44:45] op_sel_hi:[1,1,0]
	v_pk_fma_f32 v[14:15], v[10:11], v[10:11], 1.0 op_sel_hi:[1,1,0] neg_lo:[1,0,0] neg_hi:[1,0,0]
	v_pk_fma_f32 v[12:13], v[6:7], v[12:13], 0.5 op_sel_hi:[1,1,0]
	ds_write2_b32 v153, v10, v11 offset0:128 offset1:196
	v_pk_fma_f32 v[12:13], v[6:7], v[12:13], 1.0 op_sel_hi:[1,1,0]
	v_pk_add_f32 v[4:5], v[4:5], 1.0 op_sel_hi:[1,0]
	v_pk_mul_f32 v[12:13], v[12:13], v[6:7] neg_lo:[0,1] neg_hi:[0,1]
	v_rcp_f32_e32 v4, v4
	v_cndmask_b32_e32 v6, v14, v12, vcc
	v_cmp_lt_f32_e32 vcc, s25, v7
	v_sqrt_f32_e32 v6, v6
	v_rcp_f32_e32 v5, v5
	v_cndmask_b32_e32 v7, v15, v13, vcc
	v_sqrt_f32_e32 v7, v7
	v_add_u32_e32 v146, 0x1c00, v69
	v_pk_mul_f32 v[2:3], v[2:3], v[6:7]
	ds_read2_b32 v[6:7], v147 offset0:64 offset1:132
	s_waitcnt lgkmcnt(0)
	v_pk_mul_f32 v[2:3], v[2:3], v[6:7]
	ds_write2_b32 v147, v2, v3 offset0:64 offset1:132
	v_pk_add_f32 v[2:3], v[54:55], v[8:9] op_sel_hi:[0,1]
	v_pk_mul_f32 v[2:3], v[2:3], s[34:35] op_sel_hi:[1,0]
	s_nop 0
	v_exp_f32_e32 v2, v2
	v_exp_f32_e32 v3, v3
	s_nop 0
	v_pk_add_f32 v[2:3], v[2:3], 1.0 op_sel_hi:[1,0]
	s_nop 0
	v_rcp_f32_e32 v2, v2
	v_rcp_f32_e32 v3, v3
	s_nop 0
	v_pk_mul_f32 v[2:3], v[52:53], v[2:3] op_sel_hi:[0,1]
	v_pk_mul_f32 v[6:7], v[2:3], s[30:31] op_sel_hi:[1,0]
	v_pk_add_f32 v[2:3], v[2:3], v[2:3]
	v_exp_f32_e32 v6, v6
	v_pk_fma_f32 v[8:9], v[2:3], s[36:37], v[76:77] op_sel_hi:[1,0,0]
	v_exp_f32_e32 v7, v7
	v_pk_fma_f32 v[8:9], v[2:3], v[8:9], s[40:41] op_sel_hi:[1,1,0]
	v_cmp_lt_f32_e32 vcc, s25, v2
	v_pk_fma_f32 v[8:9], v[2:3], v[8:9], s[44:45] op_sel_hi:[1,1,0]
	v_pk_fma_f32 v[10:11], v[6:7], v[6:7], 1.0 op_sel_hi:[1,1,0] neg_lo:[1,0,0] neg_hi:[1,0,0]
	v_pk_fma_f32 v[8:9], v[2:3], v[8:9], 0.5 op_sel_hi:[1,1,0]
	ds_write2_b32 v146, v6, v7 offset0:8 offset1:76
	v_pk_fma_f32 v[8:9], v[2:3], v[8:9], 1.0 op_sel_hi:[1,1,0]
	s_nop 0
	v_pk_mul_f32 v[8:9], v[8:9], v[2:3] neg_lo:[0,1] neg_hi:[0,1]
	s_nop 0
	v_cndmask_b32_e32 v2, v10, v8, vcc
	v_cmp_lt_f32_e32 vcc, s25, v3
	v_sqrt_f32_e32 v2, v2
	s_nop 0
	v_cndmask_b32_e32 v3, v11, v9, vcc
	v_sqrt_f32_e32 v3, v3
	s_nop 0
	v_pk_mul_f32 v[2:3], v[4:5], v[2:3]
	ds_read2_b32 v[4:5], v145 offset0:72 offset1:140
	s_waitcnt lgkmcnt(0)
	v_pk_mul_f32 v[2:3], v[2:3], v[4:5]
	ds_write2_b32 v145, v2, v3 offset0:72 offset1:140
	v_lshlrev_b32_e32 v2, 16, v78
	v_lshlrev_b32_e32 v3, 16, v79
	v_pk_mul_f32 v[4:5], v[2:3], v[2:3]
	v_mov_b64_e32 v[78:79], s[28:29]
	s_mov_b32 s28, 0x3dd2d3e8
	v_pk_fma_f32 v[4:5], v[4:5], s[28:29], v[78:79] op_sel_hi:[1,0,0] neg_lo:[1,0,0] neg_hi:[1,0,0]
	s_nop 0
	v_pk_mul_f32 v[4:5], v[4:5], v[2:3]
	s_nop 0
	v_exp_f32_e32 v4, v4
	v_exp_f32_e32 v5, v5
	s_nop 0
	v_pk_add_f32 v[4:5], v[4:5], 1.0 op_sel_hi:[1,0]
	s_nop 0
	v_rcp_f32_e32 v4, v4
	v_rcp_f32_e32 v5, v5
	s_nop 0
	v_pk_mul_f32 v[16:17], v[4:5], v[2:3]
	v_lshlrev_b32_e32 v2, 16, v172
	v_lshlrev_b32_e32 v3, 16, v173
	v_pk_mul_f32 v[4:5], v[2:3], v[2:3]
	v_add_u32_e32 v172, 0xc0, v71
	v_pk_fma_f32 v[4:5], v[4:5], s[28:29], v[78:79] op_sel_hi:[1,0,0] neg_lo:[1,0,0] neg_hi:[1,0,0]
	v_add_u32_e32 v173, 0xd0, v71
	v_pk_mul_f32 v[4:5], v[4:5], v[2:3]
	s_nop 0
	v_exp_f32_e32 v4, v4
	v_exp_f32_e32 v5, v5
	s_nop 0
	v_pk_add_f32 v[4:5], v[4:5], 1.0 op_sel_hi:[1,0]
	s_nop 0
	v_rcp_f32_e32 v4, v4
	v_rcp_f32_e32 v5, v5
	s_nop 0
	v_pk_mul_f32 v[14:15], v[4:5], v[2:3]
	v_lshlrev_b32_e32 v2, 16, v169
	v_lshlrev_b32_e32 v3, 16, v171
	v_pk_mul_f32 v[4:5], v[2:3], v[2:3]
	v_add_u32_e32 v169, 0xa0, v71
	v_pk_fma_f32 v[4:5], v[4:5], s[28:29], v[78:79] op_sel_hi:[1,0,0] neg_lo:[1,0,0] neg_hi:[1,0,0]
	v_add_u32_e32 v171, 0xb0, v71
	v_pk_mul_f32 v[4:5], v[4:5], v[2:3]
	s_nop 0
	v_exp_f32_e32 v4, v4
	v_exp_f32_e32 v5, v5
	s_nop 0
	v_pk_add_f32 v[4:5], v[4:5], 1.0 op_sel_hi:[1,0]
	s_nop 0
	v_rcp_f32_e32 v4, v4
	v_rcp_f32_e32 v5, v5
	s_nop 0
	v_pk_mul_f32 v[12:13], v[4:5], v[2:3]
	v_lshlrev_b32_e32 v2, 16, v158
	v_lshlrev_b32_e32 v3, 16, v159
	v_pk_mul_f32 v[4:5], v[2:3], v[2:3]
	v_add_u32_e32 v158, 0x80, v71
	v_pk_fma_f32 v[4:5], v[4:5], s[28:29], v[78:79] op_sel_hi:[1,0,0] neg_lo:[1,0,0] neg_hi:[1,0,0]
	v_add_u32_e32 v159, 0x90, v71
	v_pk_mul_f32 v[4:5], v[4:5], v[2:3]
	s_nop 0
	v_exp_f32_e32 v4, v4
	v_exp_f32_e32 v5, v5
	s_nop 0
	v_pk_add_f32 v[4:5], v[4:5], 1.0 op_sel_hi:[1,0]
	s_nop 0
	v_rcp_f32_e32 v4, v4
	v_rcp_f32_e32 v5, v5
	s_nop 0
	v_pk_mul_f32 v[10:11], v[4:5], v[2:3]
	v_lshlrev_b32_e32 v2, 16, v156
	v_lshlrev_b32_e32 v3, 16, v157
	v_pk_mul_f32 v[4:5], v[2:3], v[2:3]
	v_add_u32_e32 v156, 0x60, v71
	v_pk_fma_f32 v[4:5], v[4:5], s[28:29], v[78:79] op_sel_hi:[1,0,0] neg_lo:[1,0,0] neg_hi:[1,0,0]
	v_add_u32_e32 v157, 0x70, v71
	v_pk_mul_f32 v[4:5], v[4:5], v[2:3]
	s_nop 0
	v_exp_f32_e32 v4, v4
	v_exp_f32_e32 v5, v5
	s_nop 0
	v_pk_add_f32 v[4:5], v[4:5], 1.0 op_sel_hi:[1,0]
	s_nop 0
	v_rcp_f32_e32 v4, v4
	v_rcp_f32_e32 v5, v5
	s_nop 0
	v_pk_mul_f32 v[8:9], v[4:5], v[2:3]
	v_lshlrev_b32_e32 v2, 16, v151
	v_lshlrev_b32_e32 v3, 16, v154
	v_pk_mul_f32 v[4:5], v[2:3], v[2:3]
	v_add_u32_e32 v151, 64, v71
	v_pk_fma_f32 v[4:5], v[4:5], s[28:29], v[78:79] op_sel_hi:[1,0,0] neg_lo:[1,0,0] neg_hi:[1,0,0]
	v_add_u32_e32 v154, 0x50, v71
	v_pk_mul_f32 v[4:5], v[4:5], v[2:3]
	s_nop 0
	v_exp_f32_e32 v4, v4
	v_exp_f32_e32 v5, v5
	s_nop 0
	v_pk_add_f32 v[4:5], v[4:5], 1.0 op_sel_hi:[1,0]
	s_nop 0
	v_rcp_f32_e32 v4, v4
	v_rcp_f32_e32 v5, v5
	s_nop 0
	v_pk_mul_f32 v[6:7], v[4:5], v[2:3]
	v_lshlrev_b32_e32 v2, 16, v149
	v_lshlrev_b32_e32 v3, 16, v150
	v_pk_mul_f32 v[4:5], v[2:3], v[2:3]
	v_add_u32_e32 v149, 16, v71
	v_pk_fma_f32 v[4:5], v[4:5], s[28:29], v[78:79] op_sel_hi:[1,0,0] neg_lo:[1,0,0] neg_hi:[1,0,0]
	v_add_u32_e32 v150, 48, v71
	v_pk_mul_f32 v[4:5], v[4:5], v[2:3]
	s_nop 0
	v_exp_f32_e32 v4, v4
	v_exp_f32_e32 v5, v5
	s_nop 0
	v_pk_add_f32 v[4:5], v[4:5], 1.0 op_sel_hi:[1,0]
	s_nop 0
	v_rcp_f32_e32 v4, v4
	v_rcp_f32_e32 v5, v5
	s_nop 0
	v_pk_mul_f32 v[4:5], v[4:5], v[2:3]
	v_lshlrev_b32_e32 v2, 16, v80
	v_lshlrev_b32_e32 v3, 16, v81
	v_pk_mul_f32 v[18:19], v[2:3], v[2:3]
	s_nop 0
	v_pk_fma_f32 v[18:19], v[18:19], s[28:29], v[78:79] op_sel_hi:[1,0,0] neg_lo:[1,0,0] neg_hi:[1,0,0]
	s_nop 0
	v_pk_mul_f32 v[18:19], v[18:19], v[2:3]
	s_nop 0
	v_exp_f32_e32 v18, v18
	v_exp_f32_e32 v19, v19
	s_nop 0
	v_pk_add_f32 v[18:19], v[18:19], 1.0 op_sel_hi:[1,0]
	s_nop 0
	v_rcp_f32_e32 v18, v18
	v_rcp_f32_e32 v19, v19
	s_nop 0
	v_pk_mul_f32 v[2:3], v[18:19], v[2:3]
	ds_read_b32 v19, v71 offset:6656
	ds_read_b32 v18, v127 offset:2304
	s_waitcnt lgkmcnt(0)
	v_fmac_f32_e32 v18, 0, v19
	v_pk_mul_f32 v[20:21], v[16:17], v[18:19] op_sel_hi:[0,1]
	v_cvt_pk_bf16_f32 v20, v20, v21
	global_store_short v0, v20, s[0:1]
	global_store_short_d16_hi v0, v20, s[38:39]
	ds_read2st64_b32 v[20:21], v149 offset0:10 offset1:27
	s_waitcnt lgkmcnt(0)
	v_mul_f32_e32 v19, v19, v21
	v_fmac_f32_e32 v20, v18, v21
	v_mov_b32_e32 v21, v19
	v_pk_mul_f32 v[16:17], v[16:17], v[20:21] op_sel:[1,0]
	s_nop 0
	v_cvt_pk_bf16_f32 v16, v16, v17
	global_store_short v0, v16, s[0:1] offset:2048
	global_store_short_d16_hi v0, v16, s[38:39] offset:2048
	v_add_u32_e32 v0, 32, v71
	ds_read2st64_b32 v[16:17], v0 offset0:11 offset1:28
	s_waitcnt lgkmcnt(0)
	v_mul_f32_e32 v21, v19, v17
	v_fmac_f32_e32 v16, v20, v17
	v_mov_b32_e32 v17, v21
	v_pk_mul_f32 v[18:19], v[14:15], v[16:17] op_sel_hi:[0,1]
	v_cvt_pk_bf16_f32 v17, v18, v19
	global_store_short v73, v17, s[0:1]
	global_store_short_d16_hi v73, v17, s[38:39]
	ds_read2st64_b32 v[18:19], v150 offset0:12 offset1:29
	s_waitcnt lgkmcnt(0)
	v_mul_f32_e32 v17, v21, v19
	v_fmac_f32_e32 v18, v16, v19
	v_mov_b32_e32 v19, v17
	v_pk_mul_f32 v[14:15], v[14:15], v[18:19] op_sel:[1,0]
	s_nop 0
	v_cvt_pk_bf16_f32 v14, v14, v15
	global_store_short v75, v14, s[0:1]
	global_store_short_d16_hi v75, v14, s[38:39]
	ds_read2st64_b32 v[14:15], v151 offset0:13 offset1:30
	s_waitcnt lgkmcnt(0)
	v_mul_f32_e32 v19, v17, v15
	v_fmac_f32_e32 v14, v18, v15
	v_mov_b32_e32 v15, v19
	v_pk_mul_f32 v[16:17], v[12:13], v[14:15] op_sel_hi:[0,1]
	v_cvt_pk_bf16_f32 v15, v16, v17
	global_store_short v82, v15, s[0:1]
	global_store_short_d16_hi v82, v15, s[38:39]
	ds_read2st64_b32 v[16:17], v154 offset0:14 offset1:31
	s_waitcnt lgkmcnt(0)
	v_mul_f32_e32 v15, v19, v17
	v_fmac_f32_e32 v16, v14, v17
	v_mov_b32_e32 v17, v15
	v_pk_mul_f32 v[12:13], v[12:13], v[16:17] op_sel:[1,0]
	s_nop 0
	v_cvt_pk_bf16_f32 v12, v12, v13
	global_store_short v83, v12, s[0:1]
	global_store_short_d16_hi v83, v12, s[38:39]
	ds_read2st64_b32 v[12:13], v156 offset0:15 offset1:32
	s_waitcnt lgkmcnt(0)
	v_mul_f32_e32 v17, v15, v13
	v_fmac_f32_e32 v12, v16, v13
	v_mov_b32_e32 v13, v17
	v_pk_mul_f32 v[14:15], v[10:11], v[12:13] op_sel_hi:[0,1]
	v_cvt_pk_bf16_f32 v13, v14, v15
	global_store_short v84, v13, s[0:1]
	global_store_short_d16_hi v84, v13, s[38:39]
	ds_read2st64_b32 v[14:15], v157 offset0:16 offset1:33
	s_waitcnt lgkmcnt(0)
	v_mul_f32_e32 v13, v17, v15
	v_fmac_f32_e32 v14, v12, v15
	v_mov_b32_e32 v15, v13
	v_pk_mul_f32 v[10:11], v[10:11], v[14:15] op_sel:[1,0]
	s_nop 0
	v_cvt_pk_bf16_f32 v10, v10, v11
	global_store_short v85, v10, s[0:1]
	global_store_short_d16_hi v85, v10, s[38:39]
	ds_read2st64_b32 v[10:11], v158 offset0:17 offset1:34
	s_waitcnt lgkmcnt(0)
	v_mul_f32_e32 v15, v13, v11
	v_fmac_f32_e32 v10, v14, v11
	v_mov_b32_e32 v11, v15
	v_pk_mul_f32 v[12:13], v[8:9], v[10:11] op_sel_hi:[0,1]
	v_cvt_pk_bf16_f32 v11, v12, v13
	global_store_short v86, v11, s[0:1]
	global_store_short_d16_hi v86, v11, s[38:39]
	ds_read2st64_b32 v[12:13], v159 offset0:18 offset1:35
	s_waitcnt lgkmcnt(0)
	v_mul_f32_e32 v11, v15, v13
	v_fmac_f32_e32 v12, v10, v13
	v_mov_b32_e32 v13, v11
	v_pk_mul_f32 v[8:9], v[8:9], v[12:13] op_sel:[1,0]
	s_nop 0
	v_cvt_pk_bf16_f32 v8, v8, v9
	global_store_short v87, v8, s[0:1]
	global_store_short_d16_hi v87, v8, s[38:39]
	ds_read2st64_b32 v[8:9], v169 offset0:19 offset1:36
	s_waitcnt lgkmcnt(0)
	v_mul_f32_e32 v13, v11, v9
	v_fmac_f32_e32 v8, v12, v9
	v_mov_b32_e32 v9, v13
	v_pk_mul_f32 v[10:11], v[6:7], v[8:9] op_sel_hi:[0,1]
	v_cvt_pk_bf16_f32 v9, v10, v11
	global_store_short v88, v9, s[0:1]
	global_store_short_d16_hi v88, v9, s[38:39]
	ds_read2st64_b32 v[10:11], v171 offset0:20 offset1:37
	s_waitcnt lgkmcnt(0)
	v_mul_f32_e32 v9, v13, v11
	v_fmac_f32_e32 v10, v8, v11
	v_mov_b32_e32 v11, v9
	v_pk_mul_f32 v[6:7], v[6:7], v[10:11] op_sel:[1,0]
	s_nop 0
	v_cvt_pk_bf16_f32 v6, v6, v7
	global_store_short v89, v6, s[0:1]
	global_store_short_d16_hi v89, v6, s[38:39]
	ds_read2st64_b32 v[6:7], v172 offset0:21 offset1:38
	s_waitcnt lgkmcnt(0)
	v_mul_f32_e32 v11, v9, v7
	v_fmac_f32_e32 v6, v10, v7
	v_mov_b32_e32 v7, v11
	v_pk_mul_f32 v[8:9], v[4:5], v[6:7] op_sel_hi:[0,1]
	v_cvt_pk_bf16_f32 v7, v8, v9
	global_store_short v90, v7, s[0:1]
	global_store_short_d16_hi v90, v7, s[38:39]
	ds_read2st64_b32 v[8:9], v173 offset0:22 offset1:39
	s_waitcnt lgkmcnt(0)
	v_mul_f32_e32 v7, v11, v9
	v_fmac_f32_e32 v8, v6, v9
	v_mov_b32_e32 v9, v7
	v_pk_mul_f32 v[4:5], v[4:5], v[8:9] op_sel:[1,0]
	s_nop 0
	v_cvt_pk_bf16_f32 v4, v4, v5
	global_store_short v91, v4, s[0:1]
	global_store_short_d16_hi v91, v4, s[38:39]
	ds_read2st64_b32 v[4:5], v176 offset0:23 offset1:40
	s_waitcnt lgkmcnt(0)
	v_mul_f32_e32 v9, v7, v5
	v_fmac_f32_e32 v4, v8, v5
	v_mov_b32_e32 v5, v9
	v_pk_mul_f32 v[6:7], v[2:3], v[4:5] op_sel_hi:[0,1]
	v_cvt_pk_bf16_f32 v5, v6, v7
	global_store_short v92, v5, s[0:1]
	global_store_short_d16_hi v92, v5, s[38:39]
	ds_read2st64_b32 v[80:81], v175 offset0:24 offset1:41
	s_waitcnt lgkmcnt(0)
	v_mul_f32_e32 v242, v9, v81
	v_fmac_f32_e32 v80, v4, v81
	v_mov_b32_e32 v81, v242
	v_pk_mul_f32 v[2:3], v[2:3], v[80:81] op_sel:[1,0]
	s_nop 0
	v_cvt_pk_bf16_f32 v2, v2, v3
	v_mul_f32_e32 v3, v144, v240
	v_fmac_f32_e32 v3, v141, v194
	global_store_short v93, v2, s[0:1]
	global_store_short_d16_hi v93, v2, s[38:39]
	v_lshlrev_b32_e32 v2, 16, v193
	v_fmac_f32_e32 v3, v143, v241
	v_fmac_f32_e32 v3, v128, v2
	v_add_f32_e32 v3, v129, v3
	global_load_ushort v239, v111, s[42:43]
	global_load_ushort v238, v112, s[42:43]
	global_load_ushort v237, v113, s[42:43]
	global_load_ushort v236, v114, s[42:43]
	global_load_ushort v235, v115, s[42:43]
	global_load_ushort v234, v116, s[42:43]
	global_load_ushort v233, v117, s[42:43]
	global_load_ushort v232, v118, s[42:43]
	global_load_ushort v231, v119, s[42:43]
	global_load_ushort v230, v120, s[42:43]
	global_load_ushort v229, v121, s[42:43]
	global_load_ushort v228, v122, s[42:43]
	global_load_ushort v227, v123, s[42:43]
	global_load_ushort v226, v124, s[42:43]
	global_load_ushort v225, v125, s[42:43]
	global_load_ushort v224, v126, s[42:43]
	global_load_ushort v206, v111, s[0:1]
	global_load_ushort v207, v112, s[0:1]
	global_load_ushort v202, v113, s[0:1]
	global_load_ushort v208, v114, s[0:1]
	global_load_ushort v204, v115, s[0:1]
	global_load_ushort v205, v116, s[0:1]
	global_load_ushort v200, v117, s[0:1]
	global_load_ushort v203, v118, s[0:1]
	global_load_ushort v198, v119, s[0:1]
	global_load_ushort v199, v120, s[0:1]
	global_load_ushort v193, v121, s[0:1]
	global_load_ushort v197, v122, s[0:1]
	global_load_ushort v195, v123, s[0:1]
	global_load_ushort v196, v124, s[0:1]
	global_load_ushort v194, v125, s[0:1]
	global_load_ushort v201, v126, s[0:1]
	v_cvt_pk_bf16_f32 v4, v3, v1
	ds_write_b16 v53, v4
	ds_write_b32 v127, v3 offset:2304
	v_mul_f32_e32 v4, v144, v241
	v_fmac_f32_e32 v4, v141, v240
	v_lshlrev_b32_e32 v3, 16, v223
	v_fmac_f32_e32 v4, v143, v2
	v_fmac_f32_e32 v4, v128, v3
	v_add_f32_e32 v4, v129, v4
	v_cvt_pk_bf16_f32 v5, v4, v1
	ds_write_b16 v53, v5 offset:144
	ds_write_b32 v127, v4 offset:2576
	v_mul_f32_e32 v5, v144, v2
	v_fmac_f32_e32 v5, v141, v241
	v_lshlrev_b32_e32 v4, 16, v222
	v_fmac_f32_e32 v5, v143, v3
	v_fmac_f32_e32 v5, v128, v4
	v_add_f32_e32 v5, v129, v5
	v_cvt_pk_bf16_f32 v6, v5, v1
	ds_write_b16 v53, v6 offset:288
	ds_write_b32 v127, v5 offset:2848
	v_mul_f32_e32 v6, v144, v3
	v_fmac_f32_e32 v6, v141, v2
	v_lshlrev_b32_e32 v5, 16, v221
	v_fmac_f32_e32 v6, v143, v4
	v_fmac_f32_e32 v6, v128, v5
	v_add_f32_e32 v2, v129, v6
	v_cvt_pk_bf16_f32 v6, v2, v1
	ds_write_b16 v53, v6 offset:432
	ds_write_b32 v127, v2 offset:3120
	v_mul_f32_e32 v6, v144, v4
	v_fmac_f32_e32 v6, v141, v3
	v_lshlrev_b32_e32 v2, 16, v220
	v_fmac_f32_e32 v6, v143, v5
	v_fmac_f32_e32 v6, v128, v2
	v_add_f32_e32 v3, v129, v6
	v_cvt_pk_bf16_f32 v6, v3, v1
	ds_write_b16 v53, v6 offset:576
	ds_write_b32 v127, v3 offset:3392
	v_mul_f32_e32 v6, v144, v5
	v_fmac_f32_e32 v6, v141, v4
	v_lshlrev_b32_e32 v3, 16, v219
	v_fmac_f32_e32 v6, v143, v2
	v_fmac_f32_e32 v6, v128, v3
	v_add_f32_e32 v4, v129, v6
	v_cvt_pk_bf16_f32 v6, v4, v1
	ds_write_b16 v53, v6 offset:720
	ds_write_b32 v127, v4 offset:3664
	v_mul_f32_e32 v6, v144, v2
	v_fmac_f32_e32 v6, v141, v5
	v_lshlrev_b32_e32 v4, 16, v218
	v_fmac_f32_e32 v6, v143, v3
	v_fmac_f32_e32 v6, v128, v4
	v_add_f32_e32 v5, v129, v6
	v_cvt_pk_bf16_f32 v6, v5, v1
	ds_write_b16 v53, v6 offset:864
	ds_write_b32 v127, v5 offset:3936
	v_mul_f32_e32 v6, v144, v3
	v_fmac_f32_e32 v6, v141, v2
	v_lshlrev_b32_e32 v5, 16, v217
	v_fmac_f32_e32 v6, v143, v4
	v_fmac_f32_e32 v6, v128, v5
	v_add_f32_e32 v2, v129, v6
	v_cvt_pk_bf16_f32 v6, v2, v1
	ds_write_b16 v53, v6 offset:1008
	ds_write_b32 v127, v2 offset:4208
	v_mul_f32_e32 v6, v144, v4
	v_fmac_f32_e32 v6, v141, v3
	v_lshlrev_b32_e32 v2, 16, v216
	v_fmac_f32_e32 v6, v143, v5
	v_fmac_f32_e32 v6, v128, v2
	v_add_f32_e32 v3, v129, v6
	v_cvt_pk_bf16_f32 v6, v3, v1
	ds_write_b16 v53, v6 offset:1152
	ds_write_b32 v127, v3 offset:4480
	v_mul_f32_e32 v6, v144, v5
	v_fmac_f32_e32 v6, v141, v4
	v_lshlrev_b32_e32 v3, 16, v215
	v_fmac_f32_e32 v6, v143, v2
	v_fmac_f32_e32 v6, v128, v3
	v_add_f32_e32 v4, v129, v6
	v_cvt_pk_bf16_f32 v6, v4, v1
	ds_write_b16 v53, v6 offset:1296
	ds_write_b32 v127, v4 offset:4752
	v_mul_f32_e32 v6, v144, v2
	v_fmac_f32_e32 v6, v141, v5
	v_lshlrev_b32_e32 v4, 16, v214
	v_fmac_f32_e32 v6, v143, v3
	v_fmac_f32_e32 v6, v128, v4
	v_add_f32_e32 v5, v129, v6
	v_cvt_pk_bf16_f32 v6, v5, v1
	ds_write_b16 v53, v6 offset:1440
	ds_write_b32 v127, v5 offset:5024
	v_mul_f32_e32 v6, v144, v3
	v_fmac_f32_e32 v6, v141, v2
	v_lshlrev_b32_e32 v5, 16, v213
	v_fmac_f32_e32 v6, v143, v4
	v_fmac_f32_e32 v6, v128, v5
	v_add_f32_e32 v2, v129, v6
	v_cvt_pk_bf16_f32 v6, v2, v1
	ds_write_b16 v53, v6 offset:1584
	ds_write_b32 v127, v2 offset:5296
	v_mul_f32_e32 v6, v144, v4
	v_fmac_f32_e32 v6, v141, v3
	v_lshlrev_b32_e32 v2, 16, v212
	v_fmac_f32_e32 v6, v143, v5
	v_fmac_f32_e32 v6, v128, v2
	v_add_f32_e32 v3, v129, v6
	v_cvt_pk_bf16_f32 v6, v3, v1
	ds_write_b16 v53, v6 offset:1728
	ds_write_b32 v127, v3 offset:5568
	v_mul_f32_e32 v3, v144, v5
	v_fmac_f32_e32 v3, v141, v4
	v_fmac_f32_e32 v3, v143, v2
	v_fmac_f32_e32 v3, v128, v211
	v_add_f32_e32 v3, v129, v3
	v_cvt_pk_bf16_f32 v4, v3, v1
	ds_write_b16 v53, v4 offset:1872
	ds_write_b32 v127, v3 offset:5840
	v_mul_f32_e32 v3, v144, v2
	v_fmac_f32_e32 v3, v141, v5
	v_fmac_f32_e32 v3, v143, v211
	v_fmac_f32_e32 v3, v128, v210
	v_add_f32_e32 v3, v129, v3
	v_cvt_pk_bf16_f32 v4, v3, v1
	ds_write_b16 v53, v4 offset:2016
	ds_write_b32 v127, v3 offset:6112
	v_mul_f32_e32 v3, v144, v211
	v_fmac_f32_e32 v3, v141, v2
	v_fmac_f32_e32 v3, v143, v210
	v_fmac_f32_e32 v3, v128, v209
	v_add_f32_e32 v2, v129, v3
	v_cvt_pk_bf16_f32 v3, v2, v1
	ds_write_b16 v53, v3 offset:2160
	ds_write_b32 v127, v2 offset:6384
	ds_read_b128 v[2:5], v57
	ds_read_b128 v[212:215], v57 offset:64
	ds_read_b128 v[6:9], v110
	ds_read_b128 v[10:13], v110 offset:64
	ds_read_b128 v[14:17], v110 offset:9216
	ds_read_b128 v[18:21], v110 offset:9280
	s_waitcnt lgkmcnt(3)
	v_mfma_f32_16x16x32_bf16 v[6:9], v[2:5], v[6:9], 0
	s_waitcnt lgkmcnt(2)
	v_mfma_f32_16x16x32_bf16 v[216:219], v[212:215], v[10:13], v[6:9]
	s_waitcnt lgkmcnt(1)
	v_mfma_f32_16x16x32_bf16 v[6:9], v[2:5], v[14:17], 0
	s_waitcnt lgkmcnt(0)
	v_mfma_f32_16x16x32_bf16 v[220:223], v[212:215], v[18:21], v[6:9]
	s_nop 5
	ds_read_b128 v[6:9], v110 offset:2304
	ds_read_b128 v[10:13], v110 offset:2368
	ds_read_b128 v[14:17], v110 offset:11520
	ds_read_b128 v[22:25], v110 offset:11584
	s_waitcnt lgkmcnt(3)
	v_mfma_f32_16x16x32_bf16 v[6:9], v[2:5], v[6:9], 0
	s_waitcnt lgkmcnt(2)
	v_mfma_f32_16x16x32_bf16 v[18:21], v[212:215], v[10:13], v[6:9]
	s_waitcnt lgkmcnt(1)
	v_mfma_f32_16x16x32_bf16 v[6:9], v[2:5], v[14:17], 0
	s_waitcnt lgkmcnt(0)
	v_mfma_f32_16x16x32_bf16 v[22:25], v[212:215], v[22:25], v[6:9]
	s_nop 5
	ds_read_b128 v[6:9], v110 offset:4608
	ds_read_b128 v[10:13], v110 offset:4672
	ds_read_b128 v[14:17], v110 offset:13824
	ds_read_b128 v[244:247], v110 offset:13888
	v_pk_add_f32 v[18:19], v[66:67], v[18:19] op_sel_hi:[0,1]
	v_pk_mul_f32 v[18:19], v[18:19], s[34:35] op_sel_hi:[1,0]
	s_waitcnt lgkmcnt(3)
	v_mfma_f32_16x16x32_bf16 v[6:9], v[2:5], v[6:9], 0
	v_exp_f32_e32 v18, v18
	v_exp_f32_e32 v19, v19
	v_pk_add_f32 v[22:23], v[68:69], v[22:23] op_sel_hi:[0,1]
	s_waitcnt lgkmcnt(2)
	v_mfma_f32_16x16x32_bf16 v[10:13], v[212:215], v[10:13], v[6:9]
	v_mul_f32_e64 v22, v22, s34
	v_mul_f32_e64 v23, v23, s34
	v_pk_add_f32 v[18:19], v[18:19], 1.0 op_sel_hi:[1,0]
	v_exp_f32_e32 v22, v22
	s_waitcnt lgkmcnt(1)
	v_mfma_f32_16x16x32_bf16 v[6:9], v[2:5], v[14:17], 0
	v_rcp_f32_e32 v18, v18
	v_rcp_f32_e32 v19, v19
	v_exp_f32_e32 v23, v23
	s_waitcnt lgkmcnt(0)
	v_mfma_f32_16x16x32_bf16 v[14:17], v[212:215], v[244:247], v[6:9]
	s_nop 2
	ds_read_b128 v[6:9], v110 offset:6912
	ds_read_b128 v[244:247], v110 offset:6976
	ds_read_b128 v[162:165], v110 offset:16128
	ds_read_b128 v[130:133], v110 offset:16192
	v_pk_mul_f32 v[18:19], v[64:65], v[18:19] op_sel_hi:[0,1]
	v_pk_add_f32 v[22:23], v[22:23], 1.0 op_sel_hi:[1,0]
	s_waitcnt lgkmcnt(3)
	v_mfma_f32_16x16x32_bf16 v[6:9], v[2:5], v[6:9], 0
	v_rcp_f32_e32 v22, v22
	v_rcp_f32_e32 v23, v23
	v_pk_add_f32 v[10:11], v[60:61], v[10:11] op_sel_hi:[0,1]
	s_waitcnt lgkmcnt(1)
	v_mfma_f32_16x16x32_bf16 v[2:5], v[2:5], v[162:165], 0
	v_mul_f32_e64 v10, v10, s34
	v_mul_f32_e64 v11, v11, s34
	v_pk_add_f32 v[14:15], v[62:63], v[14:15] op_sel_hi:[0,1]
	v_exp_f32_e32 v10, v10
	s_waitcnt lgkmcnt(0)
	v_mfma_f32_16x16x32_bf16 v[2:5], v[212:215], v[130:133], v[2:5]
	v_add_f32_e64 v130, v72, v216
	v_add_f32_e64 v131, v72, v217
	v_pk_mul_f32 v[130:131], v[130:131], s[34:35] op_sel_hi:[1,0]
	v_pk_add_f32 v[132:133], v[74:75], v[220:221] op_sel_hi:[0,1]
	v_exp_f32_e32 v130, v130
	v_exp_f32_e32 v131, v131
	v_pk_mul_f32 v[132:133], v[132:133], s[34:35] op_sel_hi:[1,0]
	v_mfma_f32_16x16x32_bf16 v[6:9], v[212:215], v[244:247], v[6:9]
	v_exp_f32_e32 v132, v132
	v_pk_add_f32 v[130:131], v[130:131], 1.0 op_sel_hi:[1,0]
	v_exp_f32_e32 v133, v133
	v_rcp_f32_e32 v130, v130
	v_rcp_f32_e32 v131, v131
	v_exp_f32_e32 v11, v11
	v_pk_add_f32 v[132:133], v[132:133], 1.0 op_sel_hi:[1,0]
	v_pk_mul_f32 v[14:15], v[14:15], s[34:35] op_sel_hi:[1,0]
	v_pk_mul_f32 v[130:131], v[70:71], v[130:131] op_sel_hi:[0,1]
	v_pk_mul_f32 v[162:163], v[130:131], s[30:31] op_sel_hi:[1,0]
	v_pk_add_f32 v[130:131], v[130:131], v[130:131]
	v_exp_f32_e32 v162, v162
	v_pk_fma_f32 v[164:165], v[130:131], s[36:37], v[76:77] op_sel_hi:[1,0,0]
	v_exp_f32_e32 v163, v163
	v_pk_fma_f32 v[164:165], v[130:131], v[164:165], s[40:41] op_sel_hi:[1,1,0]
	v_cmp_lt_f32_e32 vcc, s25, v130
	v_pk_fma_f32 v[164:165], v[130:131], v[164:165], s[44:45] op_sel_hi:[1,1,0]
	v_pk_fma_f32 v[212:213], v[162:163], v[162:163], 1.0 op_sel_hi:[1,1,0] neg_lo:[1,0,0] neg_hi:[1,0,0]
	v_pk_fma_f32 v[164:165], v[130:131], v[164:165], 0.5 op_sel_hi:[1,1,0]
	v_rcp_f32_e32 v132, v132
	v_pk_fma_f32 v[164:165], v[130:131], v[164:165], 1.0 op_sel_hi:[1,1,0]
	v_rcp_f32_e32 v133, v133
	v_pk_mul_f32 v[164:165], v[164:165], v[130:131] neg_lo:[0,1] neg_hi:[0,1]
	v_pk_add_f32 v[10:11], v[10:11], 1.0 op_sel_hi:[1,0]
	v_cndmask_b32_e32 v81, v212, v164, vcc
	v_cmp_lt_f32_e32 vcc, s25, v131
	v_sqrt_f32_e32 v130, v81
	v_rcp_f32_e32 v10, v10
	v_cndmask_b32_e32 v81, v213, v165, vcc
	v_sqrt_f32_e32 v131, v81
	v_rcp_f32_e32 v11, v11
	v_exp_f32_e32 v14, v14
	v_exp_f32_e32 v15, v15
	v_pk_mul_f32 v[130:131], v[132:133], v[130:131]
	ds_read2_b32 v[132:133], v174 offset0:64 offset1:80
	ds_read2_b32 v[164:165], v174 offset0:132 offset1:148
	v_pk_mul_f32 v[10:11], v[58:59], v[10:11] op_sel_hi:[0,1]
	v_pk_add_f32 v[14:15], v[14:15], 1.0 op_sel_hi:[1,0]
	v_pk_add_f32 v[6:7], v[54:55], v[6:7] op_sel_hi:[0,1]
	s_waitcnt lgkmcnt(1)
	v_mov_b32_e32 v212, v132
	s_waitcnt lgkmcnt(0)
	v_mov_b32_e32 v213, v164
	v_pk_mul_f32 v[130:131], v[212:213], v[130:131]
	ds_write_b32 v59, v130 offset:2304
	ds_write_b32 v59, v131 offset:2576
	ds_write_b32 v59, v162 offset:6656
	ds_write_b32 v59, v163 offset:6928
	v_pk_add_f32 v[130:131], v[72:73], v[218:219] op_sel_hi:[0,1]
	v_pk_mul_f32 v[130:131], v[130:131], s[34:35] op_sel_hi:[1,0]
	v_pk_add_f32 v[162:163], v[74:75], v[222:223] op_sel_hi:[0,1]
	v_exp_f32_e32 v130, v130
	v_exp_f32_e32 v131, v131
	v_pk_mul_f32 v[162:163], v[162:163], s[34:35] op_sel_hi:[1,0]
	v_mov_b32_e32 v164, v133
	v_exp_f32_e32 v162, v162
	v_pk_add_f32 v[130:131], v[130:131], 1.0 op_sel_hi:[1,0]
	v_exp_f32_e32 v163, v163
	v_rcp_f32_e32 v130, v130
	v_rcp_f32_e32 v131, v131
	v_rcp_f32_e32 v14, v14
	v_pk_add_f32 v[162:163], v[162:163], 1.0 op_sel_hi:[1,0]
	v_rcp_f32_e32 v15, v15
	v_pk_mul_f32 v[130:131], v[70:71], v[130:131] op_sel_hi:[0,1]
	v_pk_mul_f32 v[212:213], v[130:131], s[30:31] op_sel_hi:[1,0]
	v_pk_add_f32 v[130:131], v[130:131], v[130:131]
	v_exp_f32_e32 v212, v212
	v_pk_fma_f32 v[214:215], v[130:131], s[36:37], v[76:77] op_sel_hi:[1,0,0]
	v_exp_f32_e32 v213, v213
	v_pk_fma_f32 v[214:215], v[130:131], v[214:215], s[40:41] op_sel_hi:[1,1,0]
	v_cmp_lt_f32_e32 vcc, s25, v130
	v_pk_fma_f32 v[214:215], v[130:131], v[214:215], s[44:45] op_sel_hi:[1,1,0]
	v_pk_fma_f32 v[216:217], v[212:213], v[212:213], 1.0 op_sel_hi:[1,1,0] neg_lo:[1,0,0] neg_hi:[1,0,0]
	v_pk_fma_f32 v[214:215], v[130:131], v[214:215], 0.5 op_sel_hi:[1,1,0]
	v_rcp_f32_e32 v162, v162
	v_pk_fma_f32 v[214:215], v[130:131], v[214:215], 1.0 op_sel_hi:[1,1,0]
	v_rcp_f32_e32 v163, v163
	v_pk_mul_f32 v[214:215], v[214:215], v[130:131] neg_lo:[0,1] neg_hi:[0,1]
	v_pk_mul_f32 v[6:7], v[6:7], s[34:35] op_sel_hi:[1,0]
	v_cndmask_b32_e32 v81, v216, v214, vcc
	v_cmp_lt_f32_e32 vcc, s25, v131
	v_sqrt_f32_e32 v130, v81
	v_exp_f32_e32 v6, v6
	v_cndmask_b32_e32 v81, v217, v215, vcc
	v_sqrt_f32_e32 v131, v81
	v_exp_f32_e32 v7, v7
	v_pk_add_f32 v[2:3], v[56:57], v[2:3] op_sel_hi:[0,1]
	v_pk_mul_f32 v[2:3], v[2:3], s[34:35] op_sel_hi:[1,0]
	v_pk_mul_f32 v[130:131], v[162:163], v[130:131]
	ds_read2_b32 v[162:163], v148 offset0:72 offset1:140
	v_pk_add_f32 v[6:7], v[6:7], 1.0 op_sel_hi:[1,0]
	v_exp_f32_e32 v2, v2
	v_rcp_f32_e32 v6, v6
	v_rcp_f32_e32 v7, v7
	s_waitcnt lgkmcnt(0)
	v_pk_mul_f32 v[130:131], v[130:131], v[162:163]
	ds_write2_b32 v148, v130, v131 offset0:72 offset1:140
	ds_write2_b32 v167, v212, v213 offset0:8 offset1:76
	v_pk_mul_f32 v[130:131], v[18:19], s[30:31] op_sel_hi:[1,0]
	v_pk_add_f32 v[18:19], v[18:19], v[18:19]
	v_exp_f32_e32 v130, v130
	v_pk_fma_f32 v[162:163], v[18:19], s[36:37], v[76:77] op_sel_hi:[1,0,0]
	v_exp_f32_e32 v131, v131
	v_pk_fma_f32 v[162:163], v[18:19], v[162:163], s[40:41] op_sel_hi:[1,1,0]
	v_cmp_lt_f32_e32 vcc, s25, v18
	v_pk_fma_f32 v[162:163], v[18:19], v[162:163], s[44:45] op_sel_hi:[1,1,0]
	v_pk_fma_f32 v[212:213], v[130:131], v[130:131], 1.0 op_sel_hi:[1,1,0] neg_lo:[1,0,0] neg_hi:[1,0,0]
	v_pk_fma_f32 v[162:163], v[18:19], v[162:163], 0.5 op_sel_hi:[1,1,0]
	v_pk_mul_f32 v[6:7], v[52:53], v[6:7] op_sel_hi:[0,1]
	v_pk_fma_f32 v[162:163], v[18:19], v[162:163], 1.0 op_sel_hi:[1,1,0]
	v_exp_f32_e32 v3, v3
	v_pk_mul_f32 v[162:163], v[162:163], v[18:19] neg_lo:[0,1] neg_hi:[0,1]
	v_pk_add_f32 v[4:5], v[56:57], v[4:5] op_sel_hi:[0,1]
	v_cndmask_b32_e32 v18, v212, v162, vcc
	v_cmp_lt_f32_e32 vcc, s25, v19
	v_sqrt_f32_e32 v18, v18
	v_pk_add_f32 v[2:3], v[2:3], 1.0 op_sel_hi:[1,0]
	v_cndmask_b32_e32 v19, v213, v163, vcc
	v_sqrt_f32_e32 v19, v19
	v_rcp_f32_e32 v2, v2
	v_rcp_f32_e32 v3, v3
	v_pk_mul_f32 v[4:5], v[4:5], s[34:35] op_sel_hi:[1,0]
	v_pk_mul_f32 v[18:19], v[22:23], v[18:19]
	v_exp_f32_e32 v4, v4
	v_pk_mul_f32 v[18:19], v[18:19], v[164:165]
	ds_write_b32 v59, v18 offset:2368
	ds_write_b32 v59, v19 offset:2640
	ds_write_b32 v59, v130 offset:6720
	ds_write_b32 v59, v131 offset:6992
	v_pk_add_f32 v[18:19], v[66:67], v[20:21] op_sel_hi:[0,1]
	v_pk_mul_f32 v[18:19], v[18:19], s[34:35] op_sel_hi:[1,0]
	v_pk_add_f32 v[20:21], v[68:69], v[24:25] op_sel_hi:[0,1]
	v_exp_f32_e32 v18, v18
	v_exp_f32_e32 v19, v19
	v_pk_mul_f32 v[20:21], v[20:21], s[34:35] op_sel_hi:[1,0]
	v_exp_f32_e32 v5, v5
	v_exp_f32_e32 v20, v20
	v_pk_add_f32 v[18:19], v[18:19], 1.0 op_sel_hi:[1,0]
	v_exp_f32_e32 v21, v21
	v_rcp_f32_e32 v18, v18
	v_rcp_f32_e32 v19, v19
	v_pk_add_f32 v[4:5], v[4:5], 1.0 op_sel_hi:[1,0]
	v_pk_add_f32 v[20:21], v[20:21], 1.0 op_sel_hi:[1,0]
	v_rcp_f32_e32 v4, v4
	v_pk_mul_f32 v[18:19], v[64:65], v[18:19] op_sel_hi:[0,1]
	v_pk_mul_f32 v[22:23], v[18:19], s[30:31] op_sel_hi:[1,0]
	v_pk_add_f32 v[18:19], v[18:19], v[18:19]
	v_exp_f32_e32 v22, v22
	v_pk_fma_f32 v[24:25], v[18:19], s[36:37], v[76:77] op_sel_hi:[1,0,0]
	v_exp_f32_e32 v23, v23
	v_pk_fma_f32 v[24:25], v[18:19], v[24:25], s[40:41] op_sel_hi:[1,1,0]
	v_cmp_lt_f32_e32 vcc, s25, v18
	v_pk_fma_f32 v[24:25], v[18:19], v[24:25], s[44:45] op_sel_hi:[1,1,0]
	v_pk_fma_f32 v[130:131], v[22:23], v[22:23], 1.0 op_sel_hi:[1,1,0] neg_lo:[1,0,0] neg_hi:[1,0,0]
	v_pk_fma_f32 v[24:25], v[18:19], v[24:25], 0.5 op_sel_hi:[1,1,0]
	v_rcp_f32_e32 v20, v20
	v_pk_fma_f32 v[24:25], v[18:19], v[24:25], 1.0 op_sel_hi:[1,1,0]
	v_rcp_f32_e32 v21, v21
	v_pk_mul_f32 v[24:25], v[24:25], v[18:19] neg_lo:[0,1] neg_hi:[0,1]
	v_rcp_f32_e32 v5, v5
	v_cndmask_b32_e32 v18, v130, v24, vcc
	v_cmp_lt_f32_e32 vcc, s25, v19
	v_sqrt_f32_e32 v18, v18
	s_nop 0
	v_cndmask_b32_e32 v19, v131, v25, vcc
	v_sqrt_f32_e32 v19, v19
	s_nop 0
	v_pk_mul_f32 v[18:19], v[20:21], v[18:19]
	ds_read_b32 v20, v61 offset:2848
	ds_read_b32 v21, v63 offset:2848
	s_waitcnt lgkmcnt(0)
	v_pk_mul_f32 v[18:19], v[18:19], v[20:21]
	ds_write2st64_b32 v168, v18, v22 offset0:11 offset1:28
	ds_write2st64_b32 v170, v19, v23 offset0:11 offset1:28
	v_pk_mul_f32 v[18:19], v[10:11], s[30:31] op_sel_hi:[1,0]
	v_pk_add_f32 v[10:11], v[10:11], v[10:11]
	v_exp_f32_e32 v18, v18
	v_pk_fma_f32 v[20:21], v[10:11], s[36:37], v[76:77] op_sel_hi:[1,0,0]
	v_exp_f32_e32 v19, v19
	v_pk_fma_f32 v[20:21], v[10:11], v[20:21], s[40:41] op_sel_hi:[1,1,0]
	v_cmp_lt_f32_e32 vcc, s25, v10
	v_pk_fma_f32 v[20:21], v[10:11], v[20:21], s[44:45] op_sel_hi:[1,1,0]
	v_pk_fma_f32 v[22:23], v[18:19], v[18:19], 1.0 op_sel_hi:[1,1,0] neg_lo:[1,0,0] neg_hi:[1,0,0]
	v_pk_fma_f32 v[20:21], v[10:11], v[20:21], 0.5 op_sel_hi:[1,1,0]
	s_nop 0
	v_pk_fma_f32 v[20:21], v[10:11], v[20:21], 1.0 op_sel_hi:[1,1,0]
	s_nop 0
	v_pk_mul_f32 v[20:21], v[20:21], v[10:11] neg_lo:[0,1] neg_hi:[0,1]
	s_nop 0
	v_cndmask_b32_e32 v10, v22, v20, vcc
	v_cmp_lt_f32_e32 vcc, s25, v11
	v_sqrt_f32_e32 v10, v10
	s_nop 0
	v_cndmask_b32_e32 v11, v23, v21, vcc
	v_sqrt_f32_e32 v11, v11
	s_nop 0
	v_pk_mul_f32 v[10:11], v[14:15], v[10:11]
	ds_read_b32 v14, v59 offset:2432
	ds_read_b32 v15, v59 offset:2704
	s_waitcnt lgkmcnt(0)
	v_pk_mul_f32 v[10:11], v[10:11], v[14:15]
	ds_write_b32 v59, v10 offset:2432
	ds_write_b32 v59, v11 offset:2704
	ds_write_b32 v59, v18 offset:6784
	ds_write_b32 v59, v19 offset:7056
	v_pk_add_f32 v[10:11], v[60:61], v[12:13] op_sel_hi:[0,1]
	v_pk_mul_f32 v[10:11], v[10:11], s[34:35] op_sel_hi:[1,0]
	v_pk_add_f32 v[12:13], v[62:63], v[16:17] op_sel_hi:[0,1]
	v_exp_f32_e32 v10, v10
	v_exp_f32_e32 v11, v11
	v_pk_mul_f32 v[12:13], v[12:13], s[34:35] op_sel_hi:[1,0]
	v_pk_add_f32 v[10:11], v[10:11], 1.0 op_sel_hi:[1,0]
	s_nop 0
	v_rcp_f32_e32 v10, v10
	v_rcp_f32_e32 v11, v11
	v_exp_f32_e32 v12, v12
	v_exp_f32_e32 v13, v13
	v_pk_mul_f32 v[10:11], v[58:59], v[10:11] op_sel_hi:[0,1]
	v_pk_mul_f32 v[14:15], v[10:11], s[30:31] op_sel_hi:[1,0]
	v_pk_add_f32 v[10:11], v[10:11], v[10:11]
	v_exp_f32_e32 v14, v14
	v_pk_fma_f32 v[16:17], v[10:11], s[36:37], v[76:77] op_sel_hi:[1,0,0]
	v_exp_f32_e32 v15, v15
	v_pk_fma_f32 v[16:17], v[10:11], v[16:17], s[40:41] op_sel_hi:[1,1,0]
	v_cmp_lt_f32_e32 vcc, s25, v10
	v_pk_fma_f32 v[16:17], v[10:11], v[16:17], s[44:45] op_sel_hi:[1,1,0]
	v_pk_fma_f32 v[18:19], v[14:15], v[14:15], 1.0 op_sel_hi:[1,1,0] neg_lo:[1,0,0] neg_hi:[1,0,0]
	v_pk_fma_f32 v[16:17], v[10:11], v[16:17], 0.5 op_sel_hi:[1,1,0]
	v_pk_add_f32 v[12:13], v[12:13], 1.0 op_sel_hi:[1,0]
	v_pk_fma_f32 v[16:17], v[10:11], v[16:17], 1.0 op_sel_hi:[1,1,0]
	v_rcp_f32_e32 v12, v12
	v_pk_mul_f32 v[16:17], v[16:17], v[10:11] neg_lo:[0,1] neg_hi:[0,1]
	v_rcp_f32_e32 v13, v13
	v_cndmask_b32_e32 v10, v18, v16, vcc
	v_cmp_lt_f32_e32 vcc, s25, v11
	v_sqrt_f32_e32 v10, v10
	s_nop 0
	v_cndmask_b32_e32 v11, v19, v17, vcc
	v_sqrt_f32_e32 v11, v11
	s_nop 0
	v_pk_mul_f32 v[10:11], v[12:13], v[10:11]
	ds_read_b32 v12, v65 offset:2848
	ds_read_b32 v13, v67 offset:2848
	s_waitcnt lgkmcnt(0)
	v_pk_mul_f32 v[10:11], v[10:11], v[12:13]
	ds_write2st64_b32 v152, v10, v14 offset0:11 offset1:28
	ds_write2st64_b32 v155, v11, v15 offset0:11 offset1:28
	v_pk_mul_f32 v[10:11], v[6:7], s[30:31] op_sel_hi:[1,0]
	v_pk_add_f32 v[6:7], v[6:7], v[6:7]
	v_exp_f32_e32 v10, v10
	v_pk_fma_f32 v[12:13], v[6:7], s[36:37], v[76:77] op_sel_hi:[1,0,0]
	v_exp_f32_e32 v11, v11
	v_pk_fma_f32 v[12:13], v[6:7], v[12:13], s[40:41] op_sel_hi:[1,1,0]
	v_cmp_lt_f32_e32 vcc, s25, v6
	v_pk_fma_f32 v[12:13], v[6:7], v[12:13], s[44:45] op_sel_hi:[1,1,0]
	v_pk_fma_f32 v[14:15], v[10:11], v[10:11], 1.0 op_sel_hi:[1,1,0] neg_lo:[1,0,0] neg_hi:[1,0,0]
	v_pk_fma_f32 v[12:13], v[6:7], v[12:13], 0.5 op_sel_hi:[1,1,0]
	s_nop 0
	v_pk_fma_f32 v[12:13], v[6:7], v[12:13], 1.0 op_sel_hi:[1,1,0]
	s_nop 0
	v_pk_mul_f32 v[12:13], v[12:13], v[6:7] neg_lo:[0,1] neg_hi:[0,1]
	s_nop 0
	v_cndmask_b32_e32 v6, v14, v12, vcc
	v_cmp_lt_f32_e32 vcc, s25, v7
	v_sqrt_f32_e32 v6, v6
	s_nop 0
	v_cndmask_b32_e32 v7, v15, v13, vcc
	v_sqrt_f32_e32 v7, v7
	s_nop 0
	v_pk_mul_f32 v[2:3], v[2:3], v[6:7]
	ds_read2_b32 v[6:7], v147 offset0:64 offset1:132
	s_waitcnt lgkmcnt(0)
	v_pk_mul_f32 v[2:3], v[2:3], v[6:7]
	ds_write2_b32 v147, v2, v3 offset0:64 offset1:132
	ds_write2_b32 v153, v10, v11 offset0:128 offset1:196
	v_pk_add_f32 v[2:3], v[54:55], v[8:9] op_sel_hi:[0,1]
	v_pk_mul_f32 v[2:3], v[2:3], s[34:35] op_sel_hi:[1,0]
	s_nop 0
	v_exp_f32_e32 v2, v2
	v_exp_f32_e32 v3, v3
	s_nop 0
	v_pk_add_f32 v[2:3], v[2:3], 1.0 op_sel_hi:[1,0]
	s_nop 0
	v_rcp_f32_e32 v2, v2
	v_rcp_f32_e32 v3, v3
	s_nop 0
	v_pk_mul_f32 v[2:3], v[52:53], v[2:3] op_sel_hi:[0,1]
	v_pk_mul_f32 v[6:7], v[2:3], s[30:31] op_sel_hi:[1,0]
	v_pk_add_f32 v[2:3], v[2:3], v[2:3]
	v_exp_f32_e32 v6, v6
	v_pk_fma_f32 v[8:9], v[2:3], s[36:37], v[76:77] op_sel_hi:[1,0,0]
	v_exp_f32_e32 v7, v7
	v_pk_fma_f32 v[8:9], v[2:3], v[8:9], s[40:41] op_sel_hi:[1,1,0]
	v_cmp_lt_f32_e32 vcc, s25, v2
	v_pk_fma_f32 v[8:9], v[2:3], v[8:9], s[44:45] op_sel_hi:[1,1,0]
	v_pk_fma_f32 v[10:11], v[6:7], v[6:7], 1.0 op_sel_hi:[1,1,0] neg_lo:[1,0,0] neg_hi:[1,0,0]
	v_pk_fma_f32 v[8:9], v[2:3], v[8:9], 0.5 op_sel_hi:[1,1,0]
	s_nop 0
	v_pk_fma_f32 v[8:9], v[2:3], v[8:9], 1.0 op_sel_hi:[1,1,0]
	s_nop 0
	v_pk_mul_f32 v[8:9], v[8:9], v[2:3] neg_lo:[0,1] neg_hi:[0,1]
	s_nop 0
	v_cndmask_b32_e32 v2, v10, v8, vcc
	v_cmp_lt_f32_e32 vcc, s25, v3
	v_sqrt_f32_e32 v2, v2
	s_nop 0
	v_cndmask_b32_e32 v3, v11, v9, vcc
	v_sqrt_f32_e32 v3, v3
	s_nop 0
	v_pk_mul_f32 v[2:3], v[4:5], v[2:3]
	ds_read2_b32 v[4:5], v145 offset0:72 offset1:140
	s_waitcnt lgkmcnt(0)
	v_pk_mul_f32 v[2:3], v[2:3], v[4:5]
	ds_write2_b32 v145, v2, v3 offset0:72 offset1:140
	ds_write2_b32 v146, v6, v7 offset0:8 offset1:76
	s_waitcnt vmcnt(62)
	v_lshlrev_b32_e32 v2, 16, v191
	v_lshlrev_b32_e32 v3, 16, v192
	v_pk_mul_f32 v[4:5], v[2:3], v[2:3]
	s_nop 0
	v_pk_fma_f32 v[4:5], v[4:5], s[28:29], v[78:79] op_sel_hi:[1,0,0] neg_lo:[1,0,0] neg_hi:[1,0,0]
	s_nop 0
	v_pk_mul_f32 v[4:5], v[4:5], v[2:3]
	s_nop 0
	v_exp_f32_e32 v4, v4
	v_exp_f32_e32 v5, v5
	s_nop 0
	v_pk_add_f32 v[4:5], v[4:5], 1.0 op_sel_hi:[1,0]
	s_nop 0
	v_rcp_f32_e32 v4, v4
	v_rcp_f32_e32 v5, v5
	s_nop 0
	v_pk_mul_f32 v[16:17], v[4:5], v[2:3]
	v_lshlrev_b32_e32 v2, 16, v189
	v_lshlrev_b32_e32 v3, 16, v190
	v_pk_mul_f32 v[4:5], v[2:3], v[2:3]
	s_nop 0
	v_pk_fma_f32 v[4:5], v[4:5], s[28:29], v[78:79] op_sel_hi:[1,0,0] neg_lo:[1,0,0] neg_hi:[1,0,0]
	s_nop 0
	v_pk_mul_f32 v[4:5], v[4:5], v[2:3]
	s_nop 0
	v_exp_f32_e32 v4, v4
	v_exp_f32_e32 v5, v5
	s_nop 0
	v_pk_add_f32 v[4:5], v[4:5], 1.0 op_sel_hi:[1,0]
	s_nop 0
	v_rcp_f32_e32 v4, v4
	v_rcp_f32_e32 v5, v5
	s_nop 0
	v_pk_mul_f32 v[14:15], v[4:5], v[2:3]
	v_lshlrev_b32_e32 v2, 16, v187
	v_lshlrev_b32_e32 v3, 16, v188
	v_pk_mul_f32 v[4:5], v[2:3], v[2:3]
	s_nop 0
	v_pk_fma_f32 v[4:5], v[4:5], s[28:29], v[78:79] op_sel_hi:[1,0,0] neg_lo:[1,0,0] neg_hi:[1,0,0]
	s_nop 0
	v_pk_mul_f32 v[4:5], v[4:5], v[2:3]
	s_nop 0
	v_exp_f32_e32 v4, v4
	v_exp_f32_e32 v5, v5
	s_nop 0
	v_pk_add_f32 v[4:5], v[4:5], 1.0 op_sel_hi:[1,0]
	s_nop 0
	v_rcp_f32_e32 v4, v4
	v_rcp_f32_e32 v5, v5
	s_nop 0
	v_pk_mul_f32 v[12:13], v[4:5], v[2:3]
	v_lshlrev_b32_e32 v2, 16, v185
	v_lshlrev_b32_e32 v3, 16, v186
	v_pk_mul_f32 v[4:5], v[2:3], v[2:3]
	s_nop 0
	v_pk_fma_f32 v[4:5], v[4:5], s[28:29], v[78:79] op_sel_hi:[1,0,0] neg_lo:[1,0,0] neg_hi:[1,0,0]
	s_nop 0
	v_pk_mul_f32 v[4:5], v[4:5], v[2:3]
	s_nop 0
	v_exp_f32_e32 v4, v4
	v_exp_f32_e32 v5, v5
	s_nop 0
	v_pk_add_f32 v[4:5], v[4:5], 1.0 op_sel_hi:[1,0]
	s_nop 0
	v_rcp_f32_e32 v4, v4
	v_rcp_f32_e32 v5, v5
	s_nop 0
	v_pk_mul_f32 v[10:11], v[4:5], v[2:3]
	v_lshlrev_b32_e32 v2, 16, v183
	v_lshlrev_b32_e32 v3, 16, v184
	v_pk_mul_f32 v[4:5], v[2:3], v[2:3]
	s_nop 0
	v_pk_fma_f32 v[4:5], v[4:5], s[28:29], v[78:79] op_sel_hi:[1,0,0] neg_lo:[1,0,0] neg_hi:[1,0,0]
	s_nop 0
	v_pk_mul_f32 v[4:5], v[4:5], v[2:3]
	s_nop 0
	v_exp_f32_e32 v4, v4
	v_exp_f32_e32 v5, v5
	s_nop 0
	v_pk_add_f32 v[4:5], v[4:5], 1.0 op_sel_hi:[1,0]
	s_nop 0
	v_rcp_f32_e32 v4, v4
	v_rcp_f32_e32 v5, v5
	s_nop 0
	v_pk_mul_f32 v[8:9], v[4:5], v[2:3]
	v_lshlrev_b32_e32 v2, 16, v181
	v_lshlrev_b32_e32 v3, 16, v182
	v_pk_mul_f32 v[4:5], v[2:3], v[2:3]
	s_nop 0
	v_pk_fma_f32 v[4:5], v[4:5], s[28:29], v[78:79] op_sel_hi:[1,0,0] neg_lo:[1,0,0] neg_hi:[1,0,0]
	s_nop 0
	v_pk_mul_f32 v[4:5], v[4:5], v[2:3]
	s_nop 0
	v_exp_f32_e32 v4, v4
	v_exp_f32_e32 v5, v5
	s_nop 0
	v_pk_add_f32 v[4:5], v[4:5], 1.0 op_sel_hi:[1,0]
	s_nop 0
	v_rcp_f32_e32 v4, v4
	v_rcp_f32_e32 v5, v5
	s_nop 0
	v_pk_mul_f32 v[6:7], v[4:5], v[2:3]
	v_lshlrev_b32_e32 v2, 16, v179
	v_lshlrev_b32_e32 v3, 16, v180
	v_pk_mul_f32 v[4:5], v[2:3], v[2:3]
	s_nop 0
	v_pk_fma_f32 v[4:5], v[4:5], s[28:29], v[78:79] op_sel_hi:[1,0,0] neg_lo:[1,0,0] neg_hi:[1,0,0]
	s_nop 0
	v_pk_mul_f32 v[4:5], v[4:5], v[2:3]
	s_nop 0
	v_exp_f32_e32 v4, v4
	v_exp_f32_e32 v5, v5
	s_nop 0
	v_pk_add_f32 v[4:5], v[4:5], 1.0 op_sel_hi:[1,0]
	s_nop 0
	v_rcp_f32_e32 v4, v4
	v_rcp_f32_e32 v5, v5
	s_nop 0
	v_pk_mul_f32 v[4:5], v[4:5], v[2:3]
	v_lshlrev_b32_e32 v2, 16, v177
	v_lshlrev_b32_e32 v3, 16, v178
	v_pk_mul_f32 v[18:19], v[2:3], v[2:3]
	s_waitcnt vmcnt(17)
	v_lshlrev_b32_e32 v177, 16, v225
	v_pk_fma_f32 v[18:19], v[18:19], s[28:29], v[78:79] op_sel_hi:[1,0,0] neg_lo:[1,0,0] neg_hi:[1,0,0]
	s_waitcnt vmcnt(16)
	v_lshlrev_b32_e32 v178, 16, v224
	v_pk_mul_f32 v[18:19], v[18:19], v[2:3]
	s_nop 0
	v_exp_f32_e32 v18, v18
	v_exp_f32_e32 v19, v19
	s_nop 0
	v_pk_add_f32 v[18:19], v[18:19], 1.0 op_sel_hi:[1,0]
	s_nop 0
	v_rcp_f32_e32 v18, v18
	v_rcp_f32_e32 v19, v19
	s_nop 0
	v_pk_mul_f32 v[2:3], v[18:19], v[2:3]
	ds_read_b32 v19, v71 offset:6656
	ds_read_b32 v18, v127 offset:2304
	s_waitcnt lgkmcnt(0)
	v_fmac_f32_e32 v18, v80, v19
	v_mul_f32_e32 v19, v242, v19
	v_pk_mul_f32 v[20:21], v[16:17], v[18:19] op_sel_hi:[0,1]
	v_cvt_pk_bf16_f32 v20, v20, v21
	global_store_short v94, v20, s[0:1]
	global_store_short_d16_hi v94, v20, s[38:39]
	ds_read2st64_b32 v[20:21], v149 offset0:10 offset1:27
	s_waitcnt lgkmcnt(0)
	v_mul_f32_e32 v19, v19, v21
	v_fmac_f32_e32 v20, v18, v21
	v_mov_b32_e32 v21, v19
	v_pk_mul_f32 v[16:17], v[16:17], v[20:21] op_sel:[1,0]
	s_nop 0
	v_cvt_pk_bf16_f32 v16, v16, v17
	global_store_short v95, v16, s[0:1]
	global_store_short_d16_hi v95, v16, s[38:39]
	ds_read2st64_b32 v[16:17], v0 offset0:11 offset1:28
	s_waitcnt lgkmcnt(0)
	v_mul_f32_e32 v21, v19, v17
	v_fmac_f32_e32 v16, v20, v17
	v_mov_b32_e32 v17, v21
	v_pk_mul_f32 v[18:19], v[14:15], v[16:17] op_sel_hi:[0,1]
	v_cvt_pk_bf16_f32 v17, v18, v19
	global_store_short v96, v17, s[0:1]
	global_store_short_d16_hi v96, v17, s[38:39]
	ds_read2st64_b32 v[18:19], v150 offset0:12 offset1:29
	s_waitcnt lgkmcnt(0)
	v_mul_f32_e32 v17, v21, v19
	v_fmac_f32_e32 v18, v16, v19
	v_mov_b32_e32 v19, v17
	v_pk_mul_f32 v[14:15], v[14:15], v[18:19] op_sel:[1,0]
	s_nop 0
	v_cvt_pk_bf16_f32 v14, v14, v15
	global_store_short v97, v14, s[0:1]
	global_store_short_d16_hi v97, v14, s[38:39]
	ds_read2st64_b32 v[14:15], v151 offset0:13 offset1:30
	s_waitcnt lgkmcnt(0)
	v_mul_f32_e32 v19, v17, v15
	v_fmac_f32_e32 v14, v18, v15
	v_mov_b32_e32 v15, v19
	v_pk_mul_f32 v[16:17], v[12:13], v[14:15] op_sel_hi:[0,1]
	v_cvt_pk_bf16_f32 v15, v16, v17
	global_store_short v98, v15, s[0:1]
	global_store_short_d16_hi v98, v15, s[38:39]
	ds_read2st64_b32 v[16:17], v154 offset0:14 offset1:31
	s_waitcnt lgkmcnt(0)
	v_mul_f32_e32 v15, v19, v17
	v_fmac_f32_e32 v16, v14, v17
	v_mov_b32_e32 v17, v15
	v_pk_mul_f32 v[12:13], v[12:13], v[16:17] op_sel:[1,0]
	s_nop 0
	v_cvt_pk_bf16_f32 v12, v12, v13
	global_store_short v99, v12, s[0:1]
	global_store_short_d16_hi v99, v12, s[38:39]
	ds_read2st64_b32 v[12:13], v156 offset0:15 offset1:32
	s_waitcnt lgkmcnt(0)
	v_mul_f32_e32 v17, v15, v13
	v_fmac_f32_e32 v12, v16, v13
	v_mov_b32_e32 v13, v17
	v_pk_mul_f32 v[14:15], v[10:11], v[12:13] op_sel_hi:[0,1]
	v_cvt_pk_bf16_f32 v13, v14, v15
	global_store_short v100, v13, s[0:1]
	global_store_short_d16_hi v100, v13, s[38:39]
	ds_read2st64_b32 v[14:15], v157 offset0:16 offset1:33
	s_waitcnt lgkmcnt(0)
	v_mul_f32_e32 v13, v17, v15
	v_fmac_f32_e32 v14, v12, v15
	v_mov_b32_e32 v15, v13
	v_pk_mul_f32 v[10:11], v[10:11], v[14:15] op_sel:[1,0]
	s_nop 0
	v_cvt_pk_bf16_f32 v10, v10, v11
	global_store_short v101, v10, s[0:1]
	global_store_short_d16_hi v101, v10, s[38:39]
	ds_read2st64_b32 v[10:11], v158 offset0:17 offset1:34
	s_waitcnt lgkmcnt(0)
	v_mul_f32_e32 v15, v13, v11
	v_fmac_f32_e32 v10, v14, v11
	v_mov_b32_e32 v11, v15
	v_pk_mul_f32 v[12:13], v[8:9], v[10:11] op_sel_hi:[0,1]
	v_cvt_pk_bf16_f32 v11, v12, v13
	global_store_short v102, v11, s[0:1]
	global_store_short_d16_hi v102, v11, s[38:39]
	ds_read2st64_b32 v[12:13], v159 offset0:18 offset1:35
	s_waitcnt lgkmcnt(0)
	v_mul_f32_e32 v11, v15, v13
	v_fmac_f32_e32 v12, v10, v13
	v_mov_b32_e32 v13, v11
	v_pk_mul_f32 v[8:9], v[8:9], v[12:13] op_sel:[1,0]
	s_nop 0
	v_cvt_pk_bf16_f32 v8, v8, v9
	global_store_short v103, v8, s[0:1]
	global_store_short_d16_hi v103, v8, s[38:39]
	ds_read2st64_b32 v[8:9], v169 offset0:19 offset1:36
	s_waitcnt lgkmcnt(0)
	v_mul_f32_e32 v13, v11, v9
	v_fmac_f32_e32 v8, v12, v9
	v_mov_b32_e32 v9, v13
	v_pk_mul_f32 v[10:11], v[6:7], v[8:9] op_sel_hi:[0,1]
	v_cvt_pk_bf16_f32 v9, v10, v11
	global_store_short v104, v9, s[0:1]
	global_store_short_d16_hi v104, v9, s[38:39]
	ds_read2st64_b32 v[10:11], v171 offset0:20 offset1:37
	s_waitcnt lgkmcnt(0)
	v_mul_f32_e32 v9, v13, v11
	v_fmac_f32_e32 v10, v8, v11
	v_mov_b32_e32 v11, v9
	v_pk_mul_f32 v[6:7], v[6:7], v[10:11] op_sel:[1,0]
	s_nop 0
	v_cvt_pk_bf16_f32 v6, v6, v7
	global_store_short v105, v6, s[0:1]
	global_store_short_d16_hi v105, v6, s[38:39]
	ds_read2st64_b32 v[6:7], v172 offset0:21 offset1:38
	s_waitcnt lgkmcnt(0)
	v_mul_f32_e32 v11, v9, v7
	v_fmac_f32_e32 v6, v10, v7
	v_mov_b32_e32 v7, v11
	v_pk_mul_f32 v[8:9], v[4:5], v[6:7] op_sel_hi:[0,1]
	v_cvt_pk_bf16_f32 v7, v8, v9
	global_store_short v106, v7, s[0:1]
	global_store_short_d16_hi v106, v7, s[38:39]
	ds_read2st64_b32 v[8:9], v173 offset0:22 offset1:39
	s_waitcnt lgkmcnt(0)
	v_mul_f32_e32 v7, v11, v9
	v_fmac_f32_e32 v8, v6, v9
	v_mov_b32_e32 v9, v7
	v_pk_mul_f32 v[4:5], v[4:5], v[8:9] op_sel:[1,0]
	s_nop 0
	v_cvt_pk_bf16_f32 v4, v4, v5
	global_store_short v107, v4, s[0:1]
	global_store_short_d16_hi v107, v4, s[38:39]
	ds_read2st64_b32 v[4:5], v176 offset0:23 offset1:40
	s_waitcnt lgkmcnt(0)
	v_mul_f32_e32 v9, v7, v5
	v_fmac_f32_e32 v4, v8, v5
	v_mov_b32_e32 v5, v9
	v_pk_mul_f32 v[6:7], v[2:3], v[4:5] op_sel_hi:[0,1]
	v_cvt_pk_bf16_f32 v5, v6, v7
	global_store_short v108, v5, s[0:1]
	global_store_short_d16_hi v108, v5, s[38:39]
	ds_read2st64_b32 v[80:81], v175 offset0:24 offset1:41
	s_waitcnt lgkmcnt(0)
	v_mul_f32_e32 v179, v9, v81
	v_fmac_f32_e32 v80, v4, v81
	v_mov_b32_e32 v81, v179
	v_pk_mul_f32 v[2:3], v[2:3], v[80:81] op_sel:[1,0]
	v_lshlrev_b32_e32 v81, 16, v226
	v_cvt_pk_bf16_f32 v2, v2, v3
	v_mul_f32_e32 v3, v144, v210
	v_fmac_f32_e32 v3, v141, v211
	global_store_short v109, v2, s[0:1]
	global_store_short_d16_hi v109, v2, s[38:39]
	v_lshlrev_b32_e32 v2, 16, v239
	v_fmac_f32_e32 v3, v143, v209
	v_fmac_f32_e32 v3, v128, v2
	v_add_f32_e32 v3, v129, v3
	v_cvt_pk_bf16_f32 v4, v3, v1
	ds_write_b16 v53, v4
	ds_write_b32 v127, v3 offset:2304
	v_mul_f32_e32 v4, v144, v209
	v_fmac_f32_e32 v4, v141, v210
	v_lshlrev_b32_e32 v3, 16, v238
	v_fmac_f32_e32 v4, v143, v2
	v_fmac_f32_e32 v4, v128, v3
	v_add_f32_e32 v4, v129, v4
	v_cvt_pk_bf16_f32 v5, v4, v1
	ds_write_b16 v53, v5 offset:144
	ds_write_b32 v127, v4 offset:2576
	v_mul_f32_e32 v5, v144, v2
	v_fmac_f32_e32 v5, v141, v209
	v_lshlrev_b32_e32 v4, 16, v237
	v_fmac_f32_e32 v5, v143, v3
	v_fmac_f32_e32 v5, v128, v4
	v_add_f32_e32 v5, v129, v5
	v_cvt_pk_bf16_f32 v6, v5, v1
	ds_write_b16 v53, v6 offset:288
	ds_write_b32 v127, v5 offset:2848
	v_mul_f32_e32 v6, v144, v3
	v_fmac_f32_e32 v6, v141, v2
	v_lshlrev_b32_e32 v5, 16, v236
	v_fmac_f32_e32 v6, v143, v4
	v_fmac_f32_e32 v6, v128, v5
	v_add_f32_e32 v2, v129, v6
	v_cvt_pk_bf16_f32 v6, v2, v1
	ds_write_b16 v53, v6 offset:432
	ds_write_b32 v127, v2 offset:3120
	v_mul_f32_e32 v6, v144, v4
	v_fmac_f32_e32 v6, v141, v3
	v_lshlrev_b32_e32 v2, 16, v235
	v_fmac_f32_e32 v6, v143, v5
	v_fmac_f32_e32 v6, v128, v2
	v_add_f32_e32 v3, v129, v6
	v_cvt_pk_bf16_f32 v6, v3, v1
	ds_write_b16 v53, v6 offset:576
	ds_write_b32 v127, v3 offset:3392
	v_mul_f32_e32 v6, v144, v5
	v_fmac_f32_e32 v6, v141, v4
	v_lshlrev_b32_e32 v3, 16, v234
	v_fmac_f32_e32 v6, v143, v2
	v_fmac_f32_e32 v6, v128, v3
	v_add_f32_e32 v4, v129, v6
	v_cvt_pk_bf16_f32 v6, v4, v1
	ds_write_b16 v53, v6 offset:720
	ds_write_b32 v127, v4 offset:3664
	v_mul_f32_e32 v6, v144, v2
	v_fmac_f32_e32 v6, v141, v5
	v_lshlrev_b32_e32 v4, 16, v233
	v_fmac_f32_e32 v6, v143, v3
	v_fmac_f32_e32 v6, v128, v4
	v_add_f32_e32 v5, v129, v6
	v_cvt_pk_bf16_f32 v6, v5, v1
	ds_write_b16 v53, v6 offset:864
	ds_write_b32 v127, v5 offset:3936
	v_mul_f32_e32 v6, v144, v3
	v_fmac_f32_e32 v6, v141, v2
	v_lshlrev_b32_e32 v5, 16, v232
	v_fmac_f32_e32 v6, v143, v4
	v_fmac_f32_e32 v6, v128, v5
	v_add_f32_e32 v2, v129, v6
	v_cvt_pk_bf16_f32 v6, v2, v1
	ds_write_b16 v53, v6 offset:1008
	ds_write_b32 v127, v2 offset:4208
	v_mul_f32_e32 v6, v144, v4
	v_fmac_f32_e32 v6, v141, v3
	v_lshlrev_b32_e32 v2, 16, v231
	v_fmac_f32_e32 v6, v143, v5
	v_fmac_f32_e32 v6, v128, v2
	v_add_f32_e32 v3, v129, v6
	v_cvt_pk_bf16_f32 v6, v3, v1
	ds_write_b16 v53, v6 offset:1152
	ds_write_b32 v127, v3 offset:4480
	v_mul_f32_e32 v6, v144, v5
	v_fmac_f32_e32 v6, v141, v4
	v_lshlrev_b32_e32 v3, 16, v230
	v_fmac_f32_e32 v6, v143, v2
	v_fmac_f32_e32 v6, v128, v3
	v_add_f32_e32 v4, v129, v6
	v_cvt_pk_bf16_f32 v6, v4, v1
	ds_write_b16 v53, v6 offset:1296
	ds_write_b32 v127, v4 offset:4752
	v_mul_f32_e32 v6, v144, v2
	v_fmac_f32_e32 v6, v141, v5
	v_lshlrev_b32_e32 v4, 16, v229
	v_fmac_f32_e32 v6, v143, v3
	v_fmac_f32_e32 v6, v128, v4
	v_add_f32_e32 v5, v129, v6
	v_cvt_pk_bf16_f32 v6, v5, v1
	ds_write_b16 v53, v6 offset:1440
	ds_write_b32 v127, v5 offset:5024
	v_mul_f32_e32 v6, v144, v3
	v_fmac_f32_e32 v6, v141, v2
	v_lshlrev_b32_e32 v5, 16, v228
	v_fmac_f32_e32 v6, v143, v4
	v_fmac_f32_e32 v6, v128, v5
	v_add_f32_e32 v2, v129, v6
	v_cvt_pk_bf16_f32 v6, v2, v1
	ds_write_b16 v53, v6 offset:1584
	ds_write_b32 v127, v2 offset:5296
	v_mul_f32_e32 v6, v144, v4
	v_fmac_f32_e32 v6, v141, v3
	v_lshlrev_b32_e32 v2, 16, v227
	v_fmac_f32_e32 v6, v143, v5
	v_fmac_f32_e32 v6, v128, v2
	v_add_f32_e32 v3, v129, v6
	v_cvt_pk_bf16_f32 v6, v3, v1
	ds_write_b16 v53, v6 offset:1728
	ds_write_b32 v127, v3 offset:5568
	v_mul_f32_e32 v3, v144, v5
	v_fmac_f32_e32 v3, v141, v4
	v_fmac_f32_e32 v3, v143, v2
	v_fmac_f32_e32 v3, v128, v81
	v_add_f32_e32 v3, v129, v3
	v_cvt_pk_bf16_f32 v4, v3, v1
	ds_write_b16 v53, v4 offset:1872
	ds_write_b32 v127, v3 offset:5840
	v_mul_f32_e32 v3, v144, v2
	v_fmac_f32_e32 v3, v141, v5
	v_fmac_f32_e32 v3, v143, v81
	v_fmac_f32_e32 v3, v128, v177
	v_add_f32_e32 v3, v129, v3
	v_cvt_pk_bf16_f32 v4, v3, v1
	ds_write_b16 v53, v4 offset:2016
	ds_write_b32 v127, v3 offset:6112
	v_mul_f32_e32 v3, v144, v81
	v_fmac_f32_e32 v3, v141, v2
	v_fmac_f32_e32 v3, v143, v177
	v_fmac_f32_e32 v3, v128, v178
	v_add_f32_e32 v2, v129, v3
	v_cvt_pk_bf16_f32 v3, v2, v1
	ds_write_b16 v53, v3 offset:2160
	ds_write_b32 v127, v2 offset:6384
	ds_read_b128 v[2:5], v57
	ds_read_b128 v[128:131], v57 offset:64
	ds_read_b128 v[6:9], v110
	ds_read_b128 v[10:13], v110 offset:64
	ds_read_b128 v[14:17], v110 offset:9216
	ds_read_b128 v[18:21], v110 offset:9280
	s_waitcnt lgkmcnt(3)
	v_mfma_f32_16x16x32_bf16 v[6:9], v[2:5], v[6:9], 0
	s_waitcnt lgkmcnt(2)
	v_mfma_f32_16x16x32_bf16 v[162:165], v[128:131], v[10:13], v[6:9]
	s_waitcnt lgkmcnt(1)
	v_mfma_f32_16x16x32_bf16 v[6:9], v[2:5], v[14:17], 0
	s_waitcnt lgkmcnt(0)
	v_mfma_f32_16x16x32_bf16 v[180:183], v[128:131], v[18:21], v[6:9]
	s_nop 5
	ds_read_b128 v[6:9], v110 offset:2304
	ds_read_b128 v[10:13], v110 offset:2368
	ds_read_b128 v[14:17], v110 offset:11520
	ds_read_b128 v[22:25], v110 offset:11584
	s_waitcnt lgkmcnt(3)
	v_mfma_f32_16x16x32_bf16 v[6:9], v[2:5], v[6:9], 0
	s_waitcnt lgkmcnt(2)
	v_mfma_f32_16x16x32_bf16 v[18:21], v[128:131], v[10:13], v[6:9]
	s_waitcnt lgkmcnt(1)
	v_mfma_f32_16x16x32_bf16 v[6:9], v[2:5], v[14:17], 0
	s_waitcnt lgkmcnt(0)
	v_mfma_f32_16x16x32_bf16 v[22:25], v[128:131], v[22:25], v[6:9]
	s_nop 5
	ds_read_b128 v[6:9], v110 offset:4608
	ds_read_b128 v[10:13], v110 offset:4672
	ds_read_b128 v[14:17], v110 offset:13824
	ds_read_b128 v[184:187], v110 offset:13888
	v_pk_add_f32 v[18:19], v[66:67], v[18:19] op_sel_hi:[0,1]
	v_pk_mul_f32 v[18:19], v[18:19], s[34:35] op_sel_hi:[1,0]
	s_waitcnt lgkmcnt(3)
	v_mfma_f32_16x16x32_bf16 v[6:9], v[2:5], v[6:9], 0
	v_exp_f32_e32 v18, v18
	v_exp_f32_e32 v19, v19
	v_pk_add_f32 v[22:23], v[68:69], v[22:23] op_sel_hi:[0,1]
	s_waitcnt lgkmcnt(2)
	v_mfma_f32_16x16x32_bf16 v[10:13], v[128:131], v[10:13], v[6:9]
	v_mul_f32_e64 v22, v22, s34
	v_mul_f32_e64 v23, v23, s34
	v_pk_add_f32 v[18:19], v[18:19], 1.0 op_sel_hi:[1,0]
	v_exp_f32_e32 v22, v22
	s_waitcnt lgkmcnt(1)
	v_mfma_f32_16x16x32_bf16 v[6:9], v[2:5], v[14:17], 0
	v_rcp_f32_e32 v18, v18
	v_rcp_f32_e32 v19, v19
	v_exp_f32_e32 v23, v23
	s_waitcnt lgkmcnt(0)
	v_mfma_f32_16x16x32_bf16 v[14:17], v[128:131], v[184:187], v[6:9]
	s_nop 2
	ds_read_b128 v[6:9], v110 offset:6912
	ds_read_b128 v[184:187], v110 offset:6976
	ds_read_b128 v[188:191], v110 offset:16128
	ds_read_b128 v[210:213], v110 offset:16192
	v_pk_mul_f32 v[18:19], v[64:65], v[18:19] op_sel_hi:[0,1]
	v_pk_add_f32 v[22:23], v[22:23], 1.0 op_sel_hi:[1,0]
	s_waitcnt lgkmcnt(3)
	v_mfma_f32_16x16x32_bf16 v[6:9], v[2:5], v[6:9], 0
	v_rcp_f32_e32 v22, v22
	v_rcp_f32_e32 v23, v23
	v_pk_add_f32 v[10:11], v[60:61], v[10:11] op_sel_hi:[0,1]
	s_waitcnt lgkmcnt(1)
	v_mfma_f32_16x16x32_bf16 v[2:5], v[2:5], v[188:191], 0
	v_mul_f32_e64 v10, v10, s34
	v_mul_f32_e64 v11, v11, s34
	v_pk_add_f32 v[14:15], v[62:63], v[14:15] op_sel_hi:[0,1]
	v_exp_f32_e32 v10, v10
	v_mfma_f32_16x16x32_bf16 v[6:9], v[128:131], v[184:187], v[6:9]
	v_exp_f32_e32 v11, v11
	v_pk_mul_f32 v[14:15], v[14:15], s[34:35] op_sel_hi:[1,0]
	v_pk_add_f32 v[10:11], v[10:11], 1.0 op_sel_hi:[1,0]
	s_waitcnt lgkmcnt(0)
	v_mfma_f32_16x16x32_bf16 v[2:5], v[128:131], v[210:213], v[2:5]
	v_add_f32_e64 v128, v72, v162
	v_add_f32_e64 v129, v72, v163
	v_pk_mul_f32 v[128:129], v[128:129], s[34:35] op_sel_hi:[1,0]
	v_pk_add_f32 v[130:131], v[74:75], v[180:181] op_sel_hi:[0,1]
	v_exp_f32_e32 v128, v128
	v_exp_f32_e32 v129, v129
	v_pk_mul_f32 v[130:131], v[130:131], s[34:35] op_sel_hi:[1,0]
	v_rcp_f32_e32 v10, v10
	v_exp_f32_e32 v130, v130
	v_pk_add_f32 v[128:129], v[128:129], 1.0 op_sel_hi:[1,0]
	v_exp_f32_e32 v131, v131
	v_rcp_f32_e32 v128, v128
	v_rcp_f32_e32 v129, v129
	v_rcp_f32_e32 v11, v11
	v_pk_add_f32 v[130:131], v[130:131], 1.0 op_sel_hi:[1,0]
	v_exp_f32_e32 v14, v14
	v_pk_mul_f32 v[128:129], v[70:71], v[128:129] op_sel_hi:[0,1]
	v_pk_mul_f32 v[132:133], v[128:129], s[30:31] op_sel_hi:[1,0]
	v_pk_add_f32 v[128:129], v[128:129], v[128:129]
	v_exp_f32_e32 v132, v132
	v_pk_fma_f32 v[162:163], v[128:129], s[36:37], v[76:77] op_sel_hi:[1,0,0]
	v_exp_f32_e32 v133, v133
	v_pk_fma_f32 v[162:163], v[128:129], v[162:163], s[40:41] op_sel_hi:[1,1,0]
	v_cmp_lt_f32_e32 vcc, s25, v128
	v_pk_fma_f32 v[162:163], v[128:129], v[162:163], s[44:45] op_sel_hi:[1,1,0]
	v_pk_fma_f32 v[180:181], v[132:133], v[132:133], 1.0 op_sel_hi:[1,1,0] neg_lo:[1,0,0] neg_hi:[1,0,0]
	v_pk_fma_f32 v[162:163], v[128:129], v[162:163], 0.5 op_sel_hi:[1,1,0]
	v_rcp_f32_e32 v130, v130
	v_pk_fma_f32 v[162:163], v[128:129], v[162:163], 1.0 op_sel_hi:[1,1,0]
	v_rcp_f32_e32 v131, v131
	v_pk_mul_f32 v[162:163], v[162:163], v[128:129] neg_lo:[0,1] neg_hi:[0,1]
	v_pk_mul_f32 v[10:11], v[58:59], v[10:11] op_sel_hi:[0,1]
	v_cndmask_b32_e32 v128, v180, v162, vcc
	v_cmp_lt_f32_e32 vcc, s25, v129
	v_sqrt_f32_e32 v128, v128
	v_exp_f32_e32 v15, v15
	v_cndmask_b32_e32 v129, v181, v163, vcc
	v_sqrt_f32_e32 v129, v129
	v_pk_add_f32 v[6:7], v[54:55], v[6:7] op_sel_hi:[0,1]
	v_pk_add_f32 v[14:15], v[14:15], 1.0 op_sel_hi:[1,0]
	v_pk_mul_f32 v[6:7], v[6:7], s[34:35] op_sel_hi:[1,0]
	v_pk_mul_f32 v[128:129], v[130:131], v[128:129]
	ds_read2_b32 v[130:131], v174 offset0:64 offset1:80
	ds_read2_b32 v[162:163], v174 offset0:132 offset1:148
	v_rcp_f32_e32 v14, v14
	v_rcp_f32_e32 v15, v15
	v_exp_f32_e32 v6, v6
	s_waitcnt lgkmcnt(1)
	v_mov_b32_e32 v180, v130
	s_waitcnt lgkmcnt(0)
	v_mov_b32_e32 v181, v162
	v_pk_mul_f32 v[128:129], v[180:181], v[128:129]
	ds_write_b32 v59, v128 offset:2304
	ds_write_b32 v59, v129 offset:2576
	ds_write_b32 v59, v132 offset:6656
	ds_write_b32 v59, v133 offset:6928
	v_pk_add_f32 v[128:129], v[72:73], v[164:165] op_sel_hi:[0,1]
	v_pk_mul_f32 v[128:129], v[128:129], s[34:35] op_sel_hi:[1,0]
	v_pk_add_f32 v[132:133], v[74:75], v[182:183] op_sel_hi:[0,1]
	v_exp_f32_e32 v128, v128
	v_exp_f32_e32 v129, v129
	v_pk_mul_f32 v[132:133], v[132:133], s[34:35] op_sel_hi:[1,0]
	v_mov_b32_e32 v162, v131
	v_exp_f32_e32 v132, v132
	v_pk_add_f32 v[128:129], v[128:129], 1.0 op_sel_hi:[1,0]
	v_exp_f32_e32 v133, v133
	v_rcp_f32_e32 v128, v128
	v_rcp_f32_e32 v129, v129
	v_exp_f32_e32 v7, v7
	v_pk_add_f32 v[132:133], v[132:133], 1.0 op_sel_hi:[1,0]
	v_pk_add_f32 v[2:3], v[56:57], v[2:3] op_sel_hi:[0,1]
	v_pk_mul_f32 v[128:129], v[70:71], v[128:129] op_sel_hi:[0,1]
	v_pk_mul_f32 v[164:165], v[128:129], s[30:31] op_sel_hi:[1,0]
	v_pk_add_f32 v[128:129], v[128:129], v[128:129]
	v_exp_f32_e32 v164, v164
	v_pk_fma_f32 v[180:181], v[128:129], s[36:37], v[76:77] op_sel_hi:[1,0,0]
	v_exp_f32_e32 v165, v165
	v_pk_fma_f32 v[180:181], v[128:129], v[180:181], s[40:41] op_sel_hi:[1,1,0]
	v_cmp_lt_f32_e32 vcc, s25, v128
	v_pk_fma_f32 v[180:181], v[128:129], v[180:181], s[44:45] op_sel_hi:[1,1,0]
	v_pk_fma_f32 v[182:183], v[164:165], v[164:165], 1.0 op_sel_hi:[1,1,0] neg_lo:[1,0,0] neg_hi:[1,0,0]
	v_pk_fma_f32 v[180:181], v[128:129], v[180:181], 0.5 op_sel_hi:[1,1,0]
	v_rcp_f32_e32 v132, v132
	v_pk_fma_f32 v[180:181], v[128:129], v[180:181], 1.0 op_sel_hi:[1,1,0]
	v_rcp_f32_e32 v133, v133
	v_pk_mul_f32 v[180:181], v[180:181], v[128:129] neg_lo:[0,1] neg_hi:[0,1]
	v_pk_add_f32 v[6:7], v[6:7], 1.0 op_sel_hi:[1,0]
	v_cndmask_b32_e32 v70, v182, v180, vcc
	v_cmp_lt_f32_e32 vcc, s25, v129
	v_sqrt_f32_e32 v128, v70
	v_rcp_f32_e32 v6, v6
	v_cndmask_b32_e32 v70, v183, v181, vcc
	v_sqrt_f32_e32 v129, v70
	v_rcp_f32_e32 v7, v7
	v_pk_mul_f32 v[2:3], v[2:3], s[34:35] op_sel_hi:[1,0]
	v_pk_add_f32 v[4:5], v[56:57], v[4:5] op_sel_hi:[0,1]
	v_pk_mul_f32 v[128:129], v[132:133], v[128:129]
	ds_read2_b32 v[132:133], v148 offset0:72 offset1:140
	v_pk_mul_f32 v[6:7], v[52:53], v[6:7] op_sel_hi:[0,1]
	v_exp_f32_e32 v2, v2
	v_exp_f32_e32 v3, v3
	v_pk_mul_f32 v[4:5], v[4:5], s[34:35] op_sel_hi:[1,0]
	s_waitcnt lgkmcnt(0)
	v_pk_mul_f32 v[128:129], v[128:129], v[132:133]
	ds_write2_b32 v148, v128, v129 offset0:72 offset1:140
	ds_write2_b32 v167, v164, v165 offset0:8 offset1:76
	v_pk_mul_f32 v[128:129], v[18:19], s[30:31] op_sel_hi:[1,0]
	v_pk_add_f32 v[18:19], v[18:19], v[18:19]
	v_exp_f32_e32 v128, v128
	v_pk_fma_f32 v[132:133], v[18:19], s[36:37], v[76:77] op_sel_hi:[1,0,0]
	v_exp_f32_e32 v129, v129
	v_pk_fma_f32 v[132:133], v[18:19], v[132:133], s[40:41] op_sel_hi:[1,1,0]
	v_cmp_lt_f32_e32 vcc, s25, v18
	v_pk_fma_f32 v[132:133], v[18:19], v[132:133], s[44:45] op_sel_hi:[1,1,0]
	v_pk_fma_f32 v[164:165], v[128:129], v[128:129], 1.0 op_sel_hi:[1,1,0] neg_lo:[1,0,0] neg_hi:[1,0,0]
	v_pk_fma_f32 v[132:133], v[18:19], v[132:133], 0.5 op_sel_hi:[1,1,0]
	v_pk_add_f32 v[2:3], v[2:3], 1.0 op_sel_hi:[1,0]
	v_pk_fma_f32 v[132:133], v[18:19], v[132:133], 1.0 op_sel_hi:[1,1,0]
	v_rcp_f32_e32 v2, v2
	v_pk_mul_f32 v[132:133], v[132:133], v[18:19] neg_lo:[0,1] neg_hi:[0,1]
	v_rcp_f32_e32 v3, v3
	v_cndmask_b32_e32 v18, v164, v132, vcc
	v_cmp_lt_f32_e32 vcc, s25, v19
	v_sqrt_f32_e32 v18, v18
	v_exp_f32_e32 v4, v4
	v_cndmask_b32_e32 v19, v165, v133, vcc
	v_sqrt_f32_e32 v19, v19
	v_exp_f32_e32 v5, v5
	v_pk_mul_f32 v[18:19], v[22:23], v[18:19]
	s_nop 0
	v_pk_mul_f32 v[18:19], v[18:19], v[162:163]
	ds_write_b32 v59, v18 offset:2368
	ds_write_b32 v59, v19 offset:2640
	ds_write_b32 v59, v128 offset:6720
	ds_write_b32 v59, v129 offset:6992
	v_pk_add_f32 v[18:19], v[66:67], v[20:21] op_sel_hi:[0,1]
	v_pk_mul_f32 v[18:19], v[18:19], s[34:35] op_sel_hi:[1,0]
	v_pk_add_f32 v[20:21], v[68:69], v[24:25] op_sel_hi:[0,1]
	v_exp_f32_e32 v18, v18
	v_exp_f32_e32 v19, v19
	v_pk_mul_f32 v[20:21], v[20:21], s[34:35] op_sel_hi:[1,0]
	v_pk_add_f32 v[4:5], v[4:5], 1.0 op_sel_hi:[1,0]
	v_exp_f32_e32 v20, v20
	v_pk_add_f32 v[18:19], v[18:19], 1.0 op_sel_hi:[1,0]
	v_exp_f32_e32 v21, v21
	v_rcp_f32_e32 v18, v18
	v_rcp_f32_e32 v19, v19
	v_rcp_f32_e32 v4, v4
	v_pk_add_f32 v[20:21], v[20:21], 1.0 op_sel_hi:[1,0]
	v_rcp_f32_e32 v5, v5
	v_pk_mul_f32 v[18:19], v[64:65], v[18:19] op_sel_hi:[0,1]
	v_pk_mul_f32 v[22:23], v[18:19], s[30:31] op_sel_hi:[1,0]
	v_pk_add_f32 v[18:19], v[18:19], v[18:19]
	v_exp_f32_e32 v22, v22
	v_pk_fma_f32 v[24:25], v[18:19], s[36:37], v[76:77] op_sel_hi:[1,0,0]
	v_exp_f32_e32 v23, v23
	v_pk_fma_f32 v[24:25], v[18:19], v[24:25], s[40:41] op_sel_hi:[1,1,0]
	v_cmp_lt_f32_e32 vcc, s25, v18
	v_pk_fma_f32 v[24:25], v[18:19], v[24:25], s[44:45] op_sel_hi:[1,1,0]
	v_pk_fma_f32 v[128:129], v[22:23], v[22:23], 1.0 op_sel_hi:[1,1,0] neg_lo:[1,0,0] neg_hi:[1,0,0]
	v_pk_fma_f32 v[24:25], v[18:19], v[24:25], 0.5 op_sel_hi:[1,1,0]
	v_rcp_f32_e32 v20, v20
	v_pk_fma_f32 v[24:25], v[18:19], v[24:25], 1.0 op_sel_hi:[1,1,0]
	v_rcp_f32_e32 v21, v21
	v_pk_mul_f32 v[24:25], v[24:25], v[18:19] neg_lo:[0,1] neg_hi:[0,1]
	s_nop 0
	v_cndmask_b32_e32 v18, v128, v24, vcc
	v_cmp_lt_f32_e32 vcc, s25, v19
	v_sqrt_f32_e32 v18, v18
	s_nop 0
	v_cndmask_b32_e32 v19, v129, v25, vcc
	v_sqrt_f32_e32 v19, v19
	s_nop 0
	v_pk_mul_f32 v[18:19], v[20:21], v[18:19]
	ds_read_b32 v20, v61 offset:2848
	ds_read_b32 v21, v63 offset:2848
	s_waitcnt lgkmcnt(0)
	v_pk_mul_f32 v[18:19], v[18:19], v[20:21]
	ds_write2st64_b32 v168, v18, v22 offset0:11 offset1:28
	ds_write2st64_b32 v170, v19, v23 offset0:11 offset1:28
	v_pk_mul_f32 v[18:19], v[10:11], s[30:31] op_sel_hi:[1,0]
	v_pk_add_f32 v[10:11], v[10:11], v[10:11]
	v_exp_f32_e32 v18, v18
	v_pk_fma_f32 v[20:21], v[10:11], s[36:37], v[76:77] op_sel_hi:[1,0,0]
	v_exp_f32_e32 v19, v19
	v_pk_fma_f32 v[20:21], v[10:11], v[20:21], s[40:41] op_sel_hi:[1,1,0]
	v_cmp_lt_f32_e32 vcc, s25, v10
	v_pk_fma_f32 v[20:21], v[10:11], v[20:21], s[44:45] op_sel_hi:[1,1,0]
	v_pk_fma_f32 v[22:23], v[18:19], v[18:19], 1.0 op_sel_hi:[1,1,0] neg_lo:[1,0,0] neg_hi:[1,0,0]
	v_pk_fma_f32 v[20:21], v[10:11], v[20:21], 0.5 op_sel_hi:[1,1,0]
	s_nop 0
	v_pk_fma_f32 v[20:21], v[10:11], v[20:21], 1.0 op_sel_hi:[1,1,0]
	s_nop 0
	v_pk_mul_f32 v[20:21], v[20:21], v[10:11] neg_lo:[0,1] neg_hi:[0,1]
	s_nop 0
	v_cndmask_b32_e32 v10, v22, v20, vcc
	v_cmp_lt_f32_e32 vcc, s25, v11
	v_sqrt_f32_e32 v10, v10
	s_nop 0
	v_cndmask_b32_e32 v11, v23, v21, vcc
	v_sqrt_f32_e32 v11, v11
	s_nop 0
	v_pk_mul_f32 v[10:11], v[14:15], v[10:11]
	ds_read_b32 v14, v59 offset:2432
	ds_read_b32 v15, v59 offset:2704
	s_waitcnt lgkmcnt(0)
	v_pk_mul_f32 v[10:11], v[10:11], v[14:15]
	ds_write_b32 v59, v10 offset:2432
	ds_write_b32 v59, v11 offset:2704
	ds_write_b32 v59, v18 offset:6784
	ds_write_b32 v59, v19 offset:7056
	v_pk_add_f32 v[10:11], v[60:61], v[12:13] op_sel_hi:[0,1]
	v_pk_mul_f32 v[10:11], v[10:11], s[34:35] op_sel_hi:[1,0]
	v_pk_add_f32 v[12:13], v[62:63], v[16:17] op_sel_hi:[0,1]
	v_exp_f32_e32 v10, v10
	v_exp_f32_e32 v11, v11
	v_pk_mul_f32 v[12:13], v[12:13], s[34:35] op_sel_hi:[1,0]
	v_pk_add_f32 v[10:11], v[10:11], 1.0 op_sel_hi:[1,0]
	s_nop 0
	v_rcp_f32_e32 v10, v10
	v_rcp_f32_e32 v11, v11
	v_exp_f32_e32 v12, v12
	v_exp_f32_e32 v13, v13
	v_pk_mul_f32 v[10:11], v[58:59], v[10:11] op_sel_hi:[0,1]
	v_pk_mul_f32 v[14:15], v[10:11], s[30:31] op_sel_hi:[1,0]
	v_pk_add_f32 v[10:11], v[10:11], v[10:11]
	v_exp_f32_e32 v14, v14
	v_pk_fma_f32 v[16:17], v[10:11], s[36:37], v[76:77] op_sel_hi:[1,0,0]
	v_exp_f32_e32 v15, v15
	v_pk_fma_f32 v[16:17], v[10:11], v[16:17], s[40:41] op_sel_hi:[1,1,0]
	v_cmp_lt_f32_e32 vcc, s25, v10
	v_pk_fma_f32 v[16:17], v[10:11], v[16:17], s[44:45] op_sel_hi:[1,1,0]
	v_pk_fma_f32 v[18:19], v[14:15], v[14:15], 1.0 op_sel_hi:[1,1,0] neg_lo:[1,0,0] neg_hi:[1,0,0]
	v_pk_fma_f32 v[16:17], v[10:11], v[16:17], 0.5 op_sel_hi:[1,1,0]
	v_pk_add_f32 v[12:13], v[12:13], 1.0 op_sel_hi:[1,0]
	v_pk_fma_f32 v[16:17], v[10:11], v[16:17], 1.0 op_sel_hi:[1,1,0]
	v_rcp_f32_e32 v12, v12
	v_pk_mul_f32 v[16:17], v[16:17], v[10:11] neg_lo:[0,1] neg_hi:[0,1]
	v_rcp_f32_e32 v13, v13
	v_cndmask_b32_e32 v10, v18, v16, vcc
	v_cmp_lt_f32_e32 vcc, s25, v11
	v_sqrt_f32_e32 v10, v10
	s_nop 0
	v_cndmask_b32_e32 v11, v19, v17, vcc
	v_sqrt_f32_e32 v11, v11
	s_nop 0
	v_pk_mul_f32 v[10:11], v[12:13], v[10:11]
	ds_read_b32 v12, v65 offset:2848
	ds_read_b32 v13, v67 offset:2848
	s_waitcnt lgkmcnt(0)
	v_pk_mul_f32 v[10:11], v[10:11], v[12:13]
	ds_write2st64_b32 v152, v10, v14 offset0:11 offset1:28
	ds_write2st64_b32 v155, v11, v15 offset0:11 offset1:28
	v_pk_mul_f32 v[10:11], v[6:7], s[30:31] op_sel_hi:[1,0]
	v_pk_add_f32 v[6:7], v[6:7], v[6:7]
	v_exp_f32_e32 v10, v10
	v_pk_fma_f32 v[12:13], v[6:7], s[36:37], v[76:77] op_sel_hi:[1,0,0]
	v_exp_f32_e32 v11, v11
	v_pk_fma_f32 v[12:13], v[6:7], v[12:13], s[40:41] op_sel_hi:[1,1,0]
	v_cmp_lt_f32_e32 vcc, s25, v6
	v_pk_fma_f32 v[12:13], v[6:7], v[12:13], s[44:45] op_sel_hi:[1,1,0]
	v_pk_fma_f32 v[14:15], v[10:11], v[10:11], 1.0 op_sel_hi:[1,1,0] neg_lo:[1,0,0] neg_hi:[1,0,0]
	v_pk_fma_f32 v[12:13], v[6:7], v[12:13], 0.5 op_sel_hi:[1,1,0]
	s_nop 0
	v_pk_fma_f32 v[12:13], v[6:7], v[12:13], 1.0 op_sel_hi:[1,1,0]
	s_nop 0
	v_pk_mul_f32 v[12:13], v[12:13], v[6:7] neg_lo:[0,1] neg_hi:[0,1]
	s_nop 0
	v_cndmask_b32_e32 v6, v14, v12, vcc
	v_cmp_lt_f32_e32 vcc, s25, v7
	v_sqrt_f32_e32 v6, v6
	s_nop 0
	v_cndmask_b32_e32 v7, v15, v13, vcc
	v_sqrt_f32_e32 v7, v7
	s_nop 0
	v_pk_mul_f32 v[2:3], v[2:3], v[6:7]
	ds_read2_b32 v[6:7], v147 offset0:64 offset1:132
	s_waitcnt lgkmcnt(0)
	v_pk_mul_f32 v[2:3], v[2:3], v[6:7]
	ds_write2_b32 v147, v2, v3 offset0:64 offset1:132
	ds_write2_b32 v153, v10, v11 offset0:128 offset1:196
	v_pk_add_f32 v[2:3], v[54:55], v[8:9] op_sel_hi:[0,1]
	v_pk_mul_f32 v[2:3], v[2:3], s[34:35] op_sel_hi:[1,0]
	s_nop 0
	v_exp_f32_e32 v2, v2
	v_exp_f32_e32 v3, v3
	s_nop 0
	v_pk_add_f32 v[2:3], v[2:3], 1.0 op_sel_hi:[1,0]
	s_nop 0
	v_rcp_f32_e32 v2, v2
	v_rcp_f32_e32 v3, v3
	s_nop 0
	v_pk_mul_f32 v[2:3], v[52:53], v[2:3] op_sel_hi:[0,1]
	v_pk_mul_f32 v[6:7], v[2:3], s[30:31] op_sel_hi:[1,0]
	v_pk_add_f32 v[2:3], v[2:3], v[2:3]
	v_exp_f32_e32 v6, v6
	v_pk_fma_f32 v[8:9], v[2:3], s[36:37], v[76:77] op_sel_hi:[1,0,0]
	v_exp_f32_e32 v7, v7
	v_pk_fma_f32 v[8:9], v[2:3], v[8:9], s[40:41] op_sel_hi:[1,1,0]
	v_cmp_lt_f32_e32 vcc, s25, v2
	v_pk_fma_f32 v[8:9], v[2:3], v[8:9], s[44:45] op_sel_hi:[1,1,0]
	v_pk_fma_f32 v[10:11], v[6:7], v[6:7], 1.0 op_sel_hi:[1,1,0] neg_lo:[1,0,0] neg_hi:[1,0,0]
	v_pk_fma_f32 v[8:9], v[2:3], v[8:9], 0.5 op_sel_hi:[1,1,0]
	s_nop 0
	v_pk_fma_f32 v[8:9], v[2:3], v[8:9], 1.0 op_sel_hi:[1,1,0]
	s_nop 0
	v_pk_mul_f32 v[8:9], v[8:9], v[2:3] neg_lo:[0,1] neg_hi:[0,1]
	s_nop 0
	v_cndmask_b32_e32 v2, v10, v8, vcc
	v_cmp_lt_f32_e32 vcc, s25, v3
	v_sqrt_f32_e32 v2, v2
	s_nop 0
	v_cndmask_b32_e32 v3, v11, v9, vcc
	v_sqrt_f32_e32 v3, v3
	s_nop 0
	v_pk_mul_f32 v[2:3], v[4:5], v[2:3]
	ds_read2_b32 v[4:5], v145 offset0:72 offset1:140
	s_waitcnt lgkmcnt(0)
	v_pk_mul_f32 v[2:3], v[2:3], v[4:5]
	ds_write2_b32 v145, v2, v3 offset0:72 offset1:140
	ds_write2_b32 v146, v6, v7 offset0:8 offset1:76
	s_waitcnt vmcnt(47)
	v_lshlrev_b32_e32 v2, 16, v206
	s_waitcnt vmcnt(46)
	v_lshlrev_b32_e32 v3, 16, v207
	v_pk_mul_f32 v[4:5], v[2:3], v[2:3]
	s_nop 0
	v_pk_fma_f32 v[4:5], v[4:5], s[28:29], v[78:79] op_sel_hi:[1,0,0] neg_lo:[1,0,0] neg_hi:[1,0,0]
	s_nop 0
	v_pk_mul_f32 v[4:5], v[4:5], v[2:3]
	s_nop 0
	v_exp_f32_e32 v4, v4
	v_exp_f32_e32 v5, v5
	s_nop 0
	v_pk_add_f32 v[4:5], v[4:5], 1.0 op_sel_hi:[1,0]
	s_nop 0
	v_rcp_f32_e32 v4, v4
	v_rcp_f32_e32 v5, v5
	s_nop 0
	v_pk_mul_f32 v[16:17], v[4:5], v[2:3]
	s_waitcnt vmcnt(45)
	v_lshlrev_b32_e32 v2, 16, v202
	s_waitcnt vmcnt(44)
	v_lshlrev_b32_e32 v3, 16, v208
	v_pk_mul_f32 v[4:5], v[2:3], v[2:3]
	s_nop 0
	v_pk_fma_f32 v[4:5], v[4:5], s[28:29], v[78:79] op_sel_hi:[1,0,0] neg_lo:[1,0,0] neg_hi:[1,0,0]
	s_nop 0
	v_pk_mul_f32 v[4:5], v[4:5], v[2:3]
	s_nop 0
	v_exp_f32_e32 v4, v4
	v_exp_f32_e32 v5, v5
	s_nop 0
	v_pk_add_f32 v[4:5], v[4:5], 1.0 op_sel_hi:[1,0]
	s_nop 0
	v_rcp_f32_e32 v4, v4
	v_rcp_f32_e32 v5, v5
	s_nop 0
	v_pk_mul_f32 v[14:15], v[4:5], v[2:3]
	s_waitcnt vmcnt(43)
	v_lshlrev_b32_e32 v2, 16, v204
	s_waitcnt vmcnt(42)
	v_lshlrev_b32_e32 v3, 16, v205
	v_pk_mul_f32 v[4:5], v[2:3], v[2:3]
	s_nop 0
	v_pk_fma_f32 v[4:5], v[4:5], s[28:29], v[78:79] op_sel_hi:[1,0,0] neg_lo:[1,0,0] neg_hi:[1,0,0]
	s_nop 0
	v_pk_mul_f32 v[4:5], v[4:5], v[2:3]
	s_nop 0
	v_exp_f32_e32 v4, v4
	v_exp_f32_e32 v5, v5
	s_nop 0
	v_pk_add_f32 v[4:5], v[4:5], 1.0 op_sel_hi:[1,0]
	s_nop 0
	v_rcp_f32_e32 v4, v4
	v_rcp_f32_e32 v5, v5
	s_nop 0
	v_pk_mul_f32 v[12:13], v[4:5], v[2:3]
	s_waitcnt vmcnt(41)
	v_lshlrev_b32_e32 v2, 16, v200
	s_waitcnt vmcnt(40)
	v_lshlrev_b32_e32 v3, 16, v203
	v_pk_mul_f32 v[4:5], v[2:3], v[2:3]
	s_nop 0
	v_pk_fma_f32 v[4:5], v[4:5], s[28:29], v[78:79] op_sel_hi:[1,0,0] neg_lo:[1,0,0] neg_hi:[1,0,0]
	s_nop 0
	v_pk_mul_f32 v[4:5], v[4:5], v[2:3]
	s_nop 0
	v_exp_f32_e32 v4, v4
	v_exp_f32_e32 v5, v5
	s_nop 0
	v_pk_add_f32 v[4:5], v[4:5], 1.0 op_sel_hi:[1,0]
	s_nop 0
	v_rcp_f32_e32 v4, v4
	v_rcp_f32_e32 v5, v5
	s_nop 0
	v_pk_mul_f32 v[10:11], v[4:5], v[2:3]
	s_waitcnt vmcnt(39)
	v_lshlrev_b32_e32 v2, 16, v198
	s_waitcnt vmcnt(38)
	v_lshlrev_b32_e32 v3, 16, v199
	v_pk_mul_f32 v[4:5], v[2:3], v[2:3]
	s_nop 0
	v_pk_fma_f32 v[4:5], v[4:5], s[28:29], v[78:79] op_sel_hi:[1,0,0] neg_lo:[1,0,0] neg_hi:[1,0,0]
	s_nop 0
	v_pk_mul_f32 v[4:5], v[4:5], v[2:3]
	s_nop 0
	v_exp_f32_e32 v4, v4
	v_exp_f32_e32 v5, v5
	s_nop 0
	v_pk_add_f32 v[4:5], v[4:5], 1.0 op_sel_hi:[1,0]
	s_nop 0
	v_rcp_f32_e32 v4, v4
	v_rcp_f32_e32 v5, v5
	s_nop 0
	v_pk_mul_f32 v[8:9], v[4:5], v[2:3]
	s_waitcnt vmcnt(37)
	v_lshlrev_b32_e32 v2, 16, v193
	s_waitcnt vmcnt(36)
	v_lshlrev_b32_e32 v3, 16, v197
	v_pk_mul_f32 v[4:5], v[2:3], v[2:3]
	s_nop 0
	v_pk_fma_f32 v[4:5], v[4:5], s[28:29], v[78:79] op_sel_hi:[1,0,0] neg_lo:[1,0,0] neg_hi:[1,0,0]
	s_nop 0
	v_pk_mul_f32 v[4:5], v[4:5], v[2:3]
	s_nop 0
	v_exp_f32_e32 v4, v4
	v_exp_f32_e32 v5, v5
	s_nop 0
	v_pk_add_f32 v[4:5], v[4:5], 1.0 op_sel_hi:[1,0]
	s_nop 0
	v_rcp_f32_e32 v4, v4
	v_rcp_f32_e32 v5, v5
	s_nop 0
	v_pk_mul_f32 v[6:7], v[4:5], v[2:3]
	s_waitcnt vmcnt(35)
	v_lshlrev_b32_e32 v2, 16, v195
	s_waitcnt vmcnt(34)
	v_lshlrev_b32_e32 v3, 16, v196
	v_pk_mul_f32 v[4:5], v[2:3], v[2:3]
	s_nop 0
	v_pk_fma_f32 v[4:5], v[4:5], s[28:29], v[78:79] op_sel_hi:[1,0,0] neg_lo:[1,0,0] neg_hi:[1,0,0]
	s_nop 0
	v_pk_mul_f32 v[4:5], v[4:5], v[2:3]
	s_nop 0
	v_exp_f32_e32 v4, v4
	v_exp_f32_e32 v5, v5
	s_nop 0
	v_pk_add_f32 v[4:5], v[4:5], 1.0 op_sel_hi:[1,0]
	s_nop 0
	v_rcp_f32_e32 v4, v4
	v_rcp_f32_e32 v5, v5
	s_nop 0
	v_pk_mul_f32 v[4:5], v[4:5], v[2:3]
	s_waitcnt vmcnt(33)
	v_lshlrev_b32_e32 v2, 16, v194
	s_waitcnt vmcnt(32)
	v_lshlrev_b32_e32 v3, 16, v201
	v_pk_mul_f32 v[18:19], v[2:3], v[2:3]
	s_nop 0
	v_pk_fma_f32 v[18:19], v[18:19], s[28:29], v[78:79] op_sel_hi:[1,0,0] neg_lo:[1,0,0] neg_hi:[1,0,0]
	s_mul_i32 s28, s20, 43
	v_pk_mul_f32 v[18:19], v[18:19], v[2:3]
	s_mul_hi_i32 s29, s20, 43
	v_exp_f32_e32 v18, v18
	v_exp_f32_e32 v19, v19
	s_add_u32 s28, s28, s21
	s_addc_u32 s29, s29, s23
	s_lshl_b64 s[28:29], s[28:29], 13
	v_pk_add_f32 v[18:19], v[18:19], 1.0 op_sel_hi:[1,0]
	s_cmp_lg_u32 s21, 42
	v_rcp_f32_e32 v18, v18
	v_rcp_f32_e32 v19, v19
	s_nop 0
	v_pk_mul_f32 v[2:3], v[18:19], v[2:3]
	ds_read_b32 v19, v71 offset:6656
	ds_read_b32 v18, v127 offset:2304
	s_waitcnt lgkmcnt(0)
	v_fmac_f32_e32 v18, v80, v19
	v_mul_f32_e32 v19, v179, v19
	v_pk_mul_f32 v[20:21], v[16:17], v[18:19] op_sel_hi:[0,1]
	v_cvt_pk_bf16_f32 v20, v20, v21
	global_store_short v111, v20, s[0:1]
	global_store_short_d16_hi v111, v20, s[38:39]
	ds_read2st64_b32 v[20:21], v149 offset0:10 offset1:27
	s_waitcnt lgkmcnt(0)
	v_mul_f32_e32 v19, v19, v21
	v_fmac_f32_e32 v20, v18, v21
	v_mov_b32_e32 v21, v19
	v_pk_mul_f32 v[16:17], v[16:17], v[20:21] op_sel:[1,0]
	s_nop 0
	v_cvt_pk_bf16_f32 v16, v16, v17
	global_store_short v112, v16, s[0:1]
	global_store_short_d16_hi v112, v16, s[38:39]
	ds_read2st64_b32 v[16:17], v0 offset0:11 offset1:28
	s_waitcnt lgkmcnt(0)
	v_mul_f32_e32 v0, v19, v17
	v_fmac_f32_e32 v16, v20, v17
	v_mov_b32_e32 v17, v0
	v_pk_mul_f32 v[18:19], v[14:15], v[16:17] op_sel_hi:[0,1]
	v_cvt_pk_bf16_f32 v17, v18, v19
	global_store_short v113, v17, s[0:1]
	global_store_short_d16_hi v113, v17, s[38:39]
	ds_read2st64_b32 v[18:19], v150 offset0:12 offset1:29
	s_waitcnt lgkmcnt(0)
	v_mul_f32_e32 v0, v0, v19
	v_fmac_f32_e32 v18, v16, v19
	v_mov_b32_e32 v19, v0
	v_pk_mul_f32 v[14:15], v[14:15], v[18:19] op_sel:[1,0]
	s_nop 0
	v_cvt_pk_bf16_f32 v14, v14, v15
	global_store_short v114, v14, s[0:1]
	global_store_short_d16_hi v114, v14, s[38:39]
	ds_read2st64_b32 v[14:15], v151 offset0:13 offset1:30
	s_waitcnt lgkmcnt(0)
	v_mul_f32_e32 v0, v0, v15
	v_fmac_f32_e32 v14, v18, v15
	v_mov_b32_e32 v15, v0
	v_pk_mul_f32 v[16:17], v[12:13], v[14:15] op_sel_hi:[0,1]
	v_cvt_pk_bf16_f32 v15, v16, v17
	global_store_short v115, v15, s[0:1]
	global_store_short_d16_hi v115, v15, s[38:39]
	ds_read2st64_b32 v[16:17], v154 offset0:14 offset1:31
	s_waitcnt lgkmcnt(0)
	v_mul_f32_e32 v0, v0, v17
	v_fmac_f32_e32 v16, v14, v17
	v_mov_b32_e32 v17, v0
	v_pk_mul_f32 v[12:13], v[12:13], v[16:17] op_sel:[1,0]
	s_nop 0
	v_cvt_pk_bf16_f32 v12, v12, v13
	global_store_short v116, v12, s[0:1]
	global_store_short_d16_hi v116, v12, s[38:39]
	ds_read2st64_b32 v[12:13], v156 offset0:15 offset1:32
	s_waitcnt lgkmcnt(0)
	v_mul_f32_e32 v0, v0, v13
	v_fmac_f32_e32 v12, v16, v13
	v_mov_b32_e32 v13, v0
	v_pk_mul_f32 v[14:15], v[10:11], v[12:13] op_sel_hi:[0,1]
	v_cvt_pk_bf16_f32 v13, v14, v15
	global_store_short v117, v13, s[0:1]
	global_store_short_d16_hi v117, v13, s[38:39]
	ds_read2st64_b32 v[14:15], v157 offset0:16 offset1:33
	s_waitcnt lgkmcnt(0)
	v_mul_f32_e32 v0, v0, v15
	v_fmac_f32_e32 v14, v12, v15
	v_mov_b32_e32 v15, v0
	v_pk_mul_f32 v[10:11], v[10:11], v[14:15] op_sel:[1,0]
	s_nop 0
	v_cvt_pk_bf16_f32 v10, v10, v11
	global_store_short v118, v10, s[0:1]
	global_store_short_d16_hi v118, v10, s[38:39]
	ds_read2st64_b32 v[10:11], v158 offset0:17 offset1:34
	s_waitcnt lgkmcnt(0)
	v_mul_f32_e32 v0, v0, v11
	v_fmac_f32_e32 v10, v14, v11
	v_mov_b32_e32 v11, v0
	v_pk_mul_f32 v[12:13], v[8:9], v[10:11] op_sel_hi:[0,1]
	v_cvt_pk_bf16_f32 v11, v12, v13
	global_store_short v119, v11, s[0:1]
	global_store_short_d16_hi v119, v11, s[38:39]
	ds_read2st64_b32 v[12:13], v159 offset0:18 offset1:35
	s_waitcnt lgkmcnt(0)
	v_mul_f32_e32 v0, v0, v13
	v_fmac_f32_e32 v12, v10, v13
	v_mov_b32_e32 v13, v0
	v_pk_mul_f32 v[8:9], v[8:9], v[12:13] op_sel:[1,0]
	s_nop 0
	v_cvt_pk_bf16_f32 v8, v8, v9
	global_store_short v120, v8, s[0:1]
	global_store_short_d16_hi v120, v8, s[38:39]
	ds_read2st64_b32 v[8:9], v169 offset0:19 offset1:36
	s_waitcnt lgkmcnt(0)
	v_mul_f32_e32 v0, v0, v9
	v_fmac_f32_e32 v8, v12, v9
	v_mov_b32_e32 v9, v0
	v_pk_mul_f32 v[10:11], v[6:7], v[8:9] op_sel_hi:[0,1]
	v_cvt_pk_bf16_f32 v9, v10, v11
	global_store_short v121, v9, s[0:1]
	global_store_short_d16_hi v121, v9, s[38:39]
	ds_read2st64_b32 v[10:11], v171 offset0:20 offset1:37
	s_waitcnt lgkmcnt(0)
	v_mul_f32_e32 v0, v0, v11
	v_fmac_f32_e32 v10, v8, v11
	v_mov_b32_e32 v11, v0
	v_pk_mul_f32 v[6:7], v[6:7], v[10:11] op_sel:[1,0]
	s_nop 0
	v_cvt_pk_bf16_f32 v6, v6, v7
	global_store_short v122, v6, s[0:1]
	global_store_short_d16_hi v122, v6, s[38:39]
	ds_read2st64_b32 v[6:7], v172 offset0:21 offset1:38
	s_waitcnt lgkmcnt(0)
	v_mul_f32_e32 v0, v0, v7
	v_fmac_f32_e32 v6, v10, v7
	v_mov_b32_e32 v7, v0
	v_pk_mul_f32 v[8:9], v[4:5], v[6:7] op_sel_hi:[0,1]
	v_cvt_pk_bf16_f32 v7, v8, v9
	global_store_short v123, v7, s[0:1]
	global_store_short_d16_hi v123, v7, s[38:39]
	ds_read2st64_b32 v[8:9], v173 offset0:22 offset1:39
	s_waitcnt lgkmcnt(0)
	v_mul_f32_e32 v0, v0, v9
	v_fmac_f32_e32 v8, v6, v9
	v_mov_b32_e32 v9, v0
	v_pk_mul_f32 v[4:5], v[4:5], v[8:9] op_sel:[1,0]
	v_lshl_add_u64 v[6:7], v[50:51], 0, s[28:29]
	v_cvt_pk_bf16_f32 v4, v4, v5
	global_store_short v124, v4, s[0:1]
	global_store_short_d16_hi v124, v4, s[38:39]
	ds_read2st64_b32 v[4:5], v176 offset0:23 offset1:40
	s_waitcnt lgkmcnt(0)
	v_mul_f32_e32 v10, v0, v5
	v_fmac_f32_e32 v4, v8, v5
	v_mov_b32_e32 v5, v10
	v_pk_mul_f32 v[8:9], v[2:3], v[4:5] op_sel_hi:[0,1]
	v_cvt_pk_bf16_f32 v0, v8, v9
	global_store_short v125, v0, s[0:1]
	global_store_short_d16_hi v125, v0, s[38:39]
	ds_read2st64_b32 v[8:9], v175 offset0:24 offset1:41
	s_waitcnt lgkmcnt(0)
	v_mul_f32_e32 v11, v4, v9
	v_mov_b32_e32 v4, v9
	v_mov_b32_e32 v5, v8
	v_pk_mul_f32 v[8:9], v[10:11], v[4:5]
	v_pk_add_f32 v[4:5], v[10:11], v[4:5]
	v_mov_b32_e32 v10, v8
	v_mov_b32_e32 v11, v5
	v_pk_mov_b32 v[4:5], v[4:5], v[8:9] op_sel:[1,0]
	s_nop 0
	v_pk_mul_f32 v[2:3], v[2:3], v[4:5] op_sel:[1,0]
	s_nop 0
	v_cvt_pk_bf16_f32 v0, v2, v3
	global_store_short v126, v0, s[0:1]
	global_store_short_d16_hi v126, v0, s[38:39]
	global_store_dwordx2 v[6:7], v[10:11], off
	s_cbranch_scc1 .LBB0_230
	s_mul_hi_i32 s1, s20, 0x3000
	s_mulk_i32 s20, 0x3000
	s_add_u32 s0, s60, s20
	s_addc_u32 s1, s61, s1
	v_lshlrev_b32_e32 v0, 2, v26
	v_lshl_add_u64 v[2:3], s[0:1], 0, v[0:1]
	v_add_co_u32_e32 v4, vcc, 0x4090000, v2
	s_nop 1
	v_addc_co_u32_e32 v5, vcc, 0, v3, vcc
	global_store_dword v[4:5], v81, off
	v_add_co_u32_e32 v4, vcc, 0x4091000, v2
	s_nop 1
	v_addc_co_u32_e32 v5, vcc, 0, v3, vcc
	v_add_co_u32_e32 v2, vcc, 0x4092000, v2
	global_store_dword v[4:5], v177, off
	s_nop 0
	v_addc_co_u32_e32 v3, vcc, 0, v3, vcc
	global_store_dword v[2:3], v178, off
	s_branch .LBB0_230
